# gemm_in q/k-norm+rope tiles: gains/rope tables loaded once per row group (dwordx4) instead of 96 serialized reloads
# speedup vs baseline: 1.0436x; 1.0147x over previous
; DI float xsum32(float x) { auto r = __builtin_amdgcn_permlane32_swap(__float_as_uint(x), __float_as_uint(x), false, false); return __uint_as_float(r[0]) + __uint_as_float(r[1]); }
; DI float xsum16(float x) { auto r = __builtin_amdgcn_permlane16_swap(__float_as_uint(x), __float_as_uint(x), false, false); return __uint_as_float(r[0]) + __uint_as_float(r[1]); }
; template <int EPI>
; DI void gemm_epilogue(const Params& p, int layer, f32x4 (&acc)[2][2][4][2], int brow, int bcol, int pn, int wr, int wc,
;                       int fr, int fq, char* smem, int ksplit = -1) {
;     ...
; #pragma unroll
;       for (int ai = 0; ai < 2; ++ai)
; #pragma unroll
;         for (int m = 0; m < 4; ++m)
; #pragma unroll
;           for (int bj = 0; bj < 2; ++bj) {
;             float s = 0.f;
; #pragma unroll
;             for (int n = 0; n < 2; ++n)
; #pragma unroll
;               for (int j = 0; j < 4; ++j) s += acc[ai][bj][m][n][j] * acc[ai][bj][m][n][j];
;             s = xsum16(s);
;             s = xsum32(s);
;             if (fq == 0) xch[(ai * 128 + wr * 64 + m * 16 + fr) * 8 + bj * 4 + wc] = s;
;           }
.LBB0_227:
	s_and_b64 vcc, exec, s[0:1]
	s_cbranch_vccz .LBB0_373
	v_mul_f32_e32 v130, v127, v127
	v_fmac_f32_e32 v130, v126, v126
	v_fmac_f32_e32 v130, v128, v128
	v_fmac_f32_e32 v130, v129, v129
	v_fmac_f32_e32 v130, v122, v122
	v_fmac_f32_e32 v130, v123, v123
	v_fmac_f32_e32 v130, v124, v124
	v_fmac_f32_e32 v130, v125, v125
	v_mov_b32_e32 v131, v130
	s_nop 1
	v_permlane16_swap_b32_e32 v130, v131
	v_add_f32_e32 v130, v130, v131
	v_lshlrev_b32_e32 v0, 5, v160
	v_mov_b32_e32 v131, v130
	v_cmp_eq_u32_e32 vcc, 0, v161
	s_nop 0
	v_permlane32_swap_b32_e32 v130, v131
	v_add_u32_e32 v0, s17, v0
	s_and_saveexec_b64 s[0:1], vcc
	v_add_f32_e32 v130, v130, v131
	ds_write_b32 v0, v130
	s_or_b64 exec, exec, s[0:1]
	v_mul_f32_e32 v130, v119, v119
	v_fmac_f32_e32 v130, v118, v118
	v_fmac_f32_e32 v130, v120, v120
	v_fmac_f32_e32 v130, v121, v121
	v_fmac_f32_e32 v130, v114, v114
	v_fmac_f32_e32 v130, v115, v115
	v_fmac_f32_e32 v130, v116, v116
	v_fmac_f32_e32 v130, v117, v117
	v_mov_b32_e32 v131, v130
	s_nop 1
	v_permlane16_swap_b32_e32 v130, v131
	v_add_f32_e32 v130, v130, v131
	v_mov_b32_e32 v131, v130
	s_nop 1
	v_permlane32_swap_b32_e32 v130, v131
	s_and_saveexec_b64 s[0:1], vcc
	v_add_f32_e32 v130, v130, v131
	ds_write_b32 v0, v130 offset:16
	s_or_b64 exec, exec, s[0:1]
	v_mul_f32_e32 v130, v111, v111
	v_fmac_f32_e32 v130, v110, v110
	v_fmac_f32_e32 v130, v112, v112
	v_fmac_f32_e32 v130, v113, v113
	v_fmac_f32_e32 v130, v106, v106
	v_fmac_f32_e32 v130, v107, v107
	v_fmac_f32_e32 v130, v108, v108
	v_fmac_f32_e32 v130, v109, v109
	v_mov_b32_e32 v131, v130
	s_nop 1
	v_permlane16_swap_b32_e32 v130, v131
	v_add_f32_e32 v130, v130, v131
	v_mov_b32_e32 v131, v130
	s_nop 1
	v_permlane32_swap_b32_e32 v130, v131
	s_and_saveexec_b64 s[0:1], vcc
	v_add_f32_e32 v130, v130, v131
	ds_write_b32 v0, v130 offset:512
	s_or_b64 exec, exec, s[0:1]
	v_mul_f32_e32 v130, v103, v103
	v_fmac_f32_e32 v130, v102, v102
	v_fmac_f32_e32 v130, v104, v104
	v_fmac_f32_e32 v130, v105, v105
	v_fmac_f32_e32 v130, v98, v98
	v_fmac_f32_e32 v130, v99, v99
	v_fmac_f32_e32 v130, v100, v100
	v_fmac_f32_e32 v130, v101, v101
	v_mov_b32_e32 v131, v130
	s_nop 1
	v_permlane16_swap_b32_e32 v130, v131
	v_add_f32_e32 v130, v130, v131
	v_mov_b32_e32 v131, v130
	s_nop 1
	v_permlane32_swap_b32_e32 v130, v131
	s_and_saveexec_b64 s[0:1], vcc
	v_add_f32_e32 v130, v130, v131
	ds_write_b32 v0, v130 offset:528
	s_or_b64 exec, exec, s[0:1]
	v_mul_f32_e32 v130, v95, v95
	v_fmac_f32_e32 v130, v94, v94
	v_fmac_f32_e32 v130, v96, v96
	v_fmac_f32_e32 v130, v97, v97
	v_fmac_f32_e32 v130, v90, v90
	v_fmac_f32_e32 v130, v91, v91
	v_fmac_f32_e32 v130, v92, v92
	v_fmac_f32_e32 v130, v93, v93
	v_mov_b32_e32 v131, v130
	s_nop 1
	v_permlane16_swap_b32_e32 v130, v131
	v_add_f32_e32 v130, v130, v131
	v_mov_b32_e32 v131, v130
	s_nop 1
	v_permlane32_swap_b32_e32 v130, v131
	s_and_saveexec_b64 s[0:1], vcc
	v_add_f32_e32 v130, v130, v131
	ds_write_b32 v0, v130 offset:1024
	s_or_b64 exec, exec, s[0:1]
	v_mul_f32_e32 v130, v87, v87
	v_fmac_f32_e32 v130, v86, v86
	v_fmac_f32_e32 v130, v88, v88
	v_fmac_f32_e32 v130, v89, v89
	v_fmac_f32_e32 v130, v82, v82
	v_fmac_f32_e32 v130, v83, v83
	v_fmac_f32_e32 v130, v84, v84
	v_fmac_f32_e32 v130, v85, v85
	v_mov_b32_e32 v131, v130
	s_nop 1
	v_permlane16_swap_b32_e32 v130, v131
	v_add_f32_e32 v130, v130, v131
	v_mov_b32_e32 v131, v130
	s_nop 1
	v_permlane32_swap_b32_e32 v130, v131
	s_and_saveexec_b64 s[0:1], vcc
	v_add_f32_e32 v130, v130, v131
	ds_write_b32 v0, v130 offset:1040
	s_or_b64 exec, exec, s[0:1]
	v_mul_f32_e32 v130, v79, v79
	v_fmac_f32_e32 v130, v78, v78
	v_fmac_f32_e32 v130, v80, v80
	v_fmac_f32_e32 v130, v81, v81
	v_fmac_f32_e32 v130, v74, v74
	v_fmac_f32_e32 v130, v75, v75
	v_fmac_f32_e32 v130, v76, v76
	v_fmac_f32_e32 v130, v77, v77
	v_mov_b32_e32 v131, v130
	s_nop 1
	v_permlane16_swap_b32_e32 v130, v131
	v_add_f32_e32 v130, v130, v131
	v_mov_b32_e32 v131, v130
	s_nop 1
	v_permlane32_swap_b32_e32 v130, v131
	s_and_saveexec_b64 s[0:1], vcc
	v_add_f32_e32 v130, v130, v131
	ds_write_b32 v0, v130 offset:1536
	s_or_b64 exec, exec, s[0:1]
	v_mul_f32_e32 v130, v71, v71
	v_fmac_f32_e32 v130, v70, v70
	v_fmac_f32_e32 v130, v72, v72
	v_fmac_f32_e32 v130, v73, v73
	v_fmac_f32_e32 v130, v66, v66
	v_fmac_f32_e32 v130, v67, v67
	v_fmac_f32_e32 v130, v68, v68
	v_fmac_f32_e32 v130, v69, v69
	v_mov_b32_e32 v131, v130
	s_nop 1
	v_permlane16_swap_b32_e32 v130, v131
	v_add_f32_e32 v130, v130, v131
	v_mov_b32_e32 v131, v130
	s_nop 1
	v_permlane32_swap_b32_e32 v130, v131
	s_and_saveexec_b64 s[0:1], vcc
	v_add_f32_e32 v130, v130, v131
	ds_write_b32 v0, v130 offset:1552
	s_or_b64 exec, exec, s[0:1]
	v_mul_f32_e32 v130, v63, v63
	v_fmac_f32_e32 v130, v62, v62
	v_fmac_f32_e32 v130, v64, v64
	v_fmac_f32_e32 v130, v65, v65
	v_fmac_f32_e32 v130, v58, v58
	v_fmac_f32_e32 v130, v59, v59
	v_fmac_f32_e32 v130, v60, v60
	v_fmac_f32_e32 v130, v61, v61
	v_mov_b32_e32 v131, v130
	s_nop 1
	v_permlane16_swap_b32_e32 v130, v131
	v_add_f32_e32 v130, v130, v131
	v_mov_b32_e32 v131, v130
	s_nop 1
	v_permlane32_swap_b32_e32 v130, v131
	s_and_saveexec_b64 s[0:1], vcc
	v_add_f32_e32 v130, v130, v131
	ds_write_b32 v0, v130 offset:4096
	s_or_b64 exec, exec, s[0:1]
	v_mul_f32_e32 v130, v55, v55
	v_fmac_f32_e32 v130, v54, v54
	v_fmac_f32_e32 v130, v56, v56
	v_fmac_f32_e32 v130, v57, v57
	v_fmac_f32_e32 v130, v50, v50
	v_fmac_f32_e32 v130, v51, v51
	v_fmac_f32_e32 v130, v52, v52
	v_fmac_f32_e32 v130, v53, v53
	v_mov_b32_e32 v131, v130
	s_nop 1
	v_permlane16_swap_b32_e32 v130, v131
	v_add_f32_e32 v130, v130, v131
	v_mov_b32_e32 v131, v130
	s_nop 1
	v_permlane32_swap_b32_e32 v130, v131
	s_and_saveexec_b64 s[0:1], vcc
; template <int EPI>
; DI void gemm_epilogue(const Params& p, int layer, f32x4 (&acc)[2][2][4][2], int brow, int bcol, int pn, int wr, int wc,
;                       int fr, int fq, char* smem, int ksplit = -1) {
;     ...
;       __syncthreads();
;       const float* gq = (pn == 9 ? p.qn_g : p.kn_g) + layer * 64;
; #pragma unroll
;       for (int ai = 0; ai < 2; ++ai)
; #pragma unroll
;         for (int m = 0; m < 4; ++m) {
;           __builtin_amdgcn_sched_barrier(0);
;           const int rl = ai * 128 + wr * 64 + m * 16 + fr;
;           const int row = brow + rl;
;           const int spos = row & (SEQ - 1);
; #pragma unroll
;           for (int bj = 0; bj < 2; ++bj) {
;             const bool normed = (pn == 9) || (bj == 0);
;             float rs = 1.f;
;             if (normed) {
;               float tot = xch[rl * 8 + bj * 4 + wc] + xch[rl * 8 + bj * 4 + (wc ^ 1)];
;               rs = __builtin_amdgcn_rsqf(tot * (1.f / 64.f) + EPSN);
;             }
;             u32x4 o;
; #pragma unroll
;             for (int n = 0; n < 2; ++n) {
;               const int cih = (wc & 1) * 32 + fq * 8 + n * 4;
;               f32x4 v = acc[ai][bj][m][n];
;               if (normed) {
;                 f32x4 g = *(const f32x4*)(gq + cih);
;                 v = v * rs * g;
;                 if (latent) {
;                   const float2 cs = *(const float2*)(p.ropec + spos * 32 + (cih >> 1));
;                   const float2 sn = *(const float2*)(p.ropes + spos * 32 + (cih >> 1));
	v_add_f32_e32 v130, v130, v131
	ds_write_b32 v0, v130 offset:4112
	s_or_b64 exec, exec, s[0:1]
	v_mul_f32_e32 v130, v47, v47
	v_fmac_f32_e32 v130, v46, v46
	v_fmac_f32_e32 v130, v48, v48
	v_fmac_f32_e32 v130, v49, v49
	v_fmac_f32_e32 v130, v42, v42
	v_fmac_f32_e32 v130, v43, v43
	v_fmac_f32_e32 v130, v44, v44
	v_fmac_f32_e32 v130, v45, v45
	v_mov_b32_e32 v131, v130
	s_nop 1
	v_permlane16_swap_b32_e32 v130, v131
	v_add_f32_e32 v130, v130, v131
	v_mov_b32_e32 v131, v130
	s_nop 1
	v_permlane32_swap_b32_e32 v130, v131
	s_and_saveexec_b64 s[0:1], vcc
	v_add_f32_e32 v130, v130, v131
	ds_write_b32 v0, v130 offset:4608
	s_or_b64 exec, exec, s[0:1]
	v_mul_f32_e32 v130, v39, v39
	v_fmac_f32_e32 v130, v38, v38
	v_fmac_f32_e32 v130, v40, v40
	v_fmac_f32_e32 v130, v41, v41
	v_fmac_f32_e32 v130, v34, v34
	v_fmac_f32_e32 v130, v35, v35
	v_fmac_f32_e32 v130, v36, v36
	v_fmac_f32_e32 v130, v37, v37
	v_mov_b32_e32 v131, v130
	s_nop 1
	v_permlane16_swap_b32_e32 v130, v131
	v_add_f32_e32 v130, v130, v131
	v_mov_b32_e32 v131, v130
	s_nop 1
	v_permlane32_swap_b32_e32 v130, v131
	s_and_saveexec_b64 s[0:1], vcc
	v_add_f32_e32 v130, v130, v131
	ds_write_b32 v0, v130 offset:4624
	s_or_b64 exec, exec, s[0:1]
	v_mul_f32_e32 v130, v31, v31
	v_fmac_f32_e32 v130, v30, v30
	v_fmac_f32_e32 v130, v32, v32
	v_fmac_f32_e32 v130, v33, v33
	v_fmac_f32_e32 v130, v26, v26
	v_fmac_f32_e32 v130, v27, v27
	v_fmac_f32_e32 v130, v28, v28
	v_fmac_f32_e32 v130, v29, v29
	v_mov_b32_e32 v131, v130
	s_nop 1
	v_permlane16_swap_b32_e32 v130, v131
	v_add_f32_e32 v130, v130, v131
	v_mov_b32_e32 v131, v130
	s_nop 1
	v_permlane32_swap_b32_e32 v130, v131
	s_and_saveexec_b64 s[0:1], vcc
	v_add_f32_e32 v130, v130, v131
	ds_write_b32 v0, v130 offset:5120
	s_or_b64 exec, exec, s[0:1]
	v_mul_f32_e32 v130, v23, v23
	v_fmac_f32_e32 v130, v22, v22
	v_fmac_f32_e32 v130, v24, v24
	v_fmac_f32_e32 v130, v25, v25
	v_fmac_f32_e32 v130, v18, v18
	v_fmac_f32_e32 v130, v19, v19
	v_fmac_f32_e32 v130, v20, v20
	v_fmac_f32_e32 v130, v21, v21
	v_mov_b32_e32 v131, v130
	s_nop 1
	v_permlane16_swap_b32_e32 v130, v131
	v_add_f32_e32 v130, v130, v131
	v_mov_b32_e32 v131, v130
	s_nop 1
	v_permlane32_swap_b32_e32 v130, v131
	s_and_saveexec_b64 s[0:1], vcc
	v_add_f32_e32 v130, v130, v131
	ds_write_b32 v0, v130 offset:5136
	s_or_b64 exec, exec, s[0:1]
	v_mul_f32_e32 v130, v15, v15
	v_fmac_f32_e32 v130, v14, v14
	v_fmac_f32_e32 v130, v16, v16
	v_fmac_f32_e32 v130, v17, v17
	v_fmac_f32_e32 v130, v10, v10
	v_fmac_f32_e32 v130, v11, v11
	v_fmac_f32_e32 v130, v12, v12
	v_fmac_f32_e32 v130, v13, v13
	v_mov_b32_e32 v131, v130
	s_nop 1
	v_permlane16_swap_b32_e32 v130, v131
	v_add_f32_e32 v130, v130, v131
	v_mov_b32_e32 v131, v130
	s_nop 1
	v_permlane32_swap_b32_e32 v130, v131
	s_and_saveexec_b64 s[0:1], vcc
	v_add_f32_e32 v130, v130, v131
	ds_write_b32 v0, v130 offset:5632
	s_or_b64 exec, exec, s[0:1]
	v_mul_f32_e32 v130, v7, v7
	v_fmac_f32_e32 v130, v6, v6
	v_fmac_f32_e32 v130, v8, v8
	v_fmac_f32_e32 v130, v9, v9
	v_fmac_f32_e32 v130, v2, v2
	v_fmac_f32_e32 v130, v3, v3
	v_fmac_f32_e32 v130, v4, v4
	v_fmac_f32_e32 v130, v5, v5
	v_mov_b32_e32 v131, v130
	s_nop 1
	v_permlane16_swap_b32_e32 v130, v131
	v_add_f32_e32 v130, v130, v131
	v_mov_b32_e32 v131, v130
	s_nop 1
	v_permlane32_swap_b32_e32 v130, v131
	s_and_saveexec_b64 s[0:1], vcc
	v_add_f32_e32 v130, v130, v131
	ds_write_b32 v0, v130 offset:5648
	s_or_b64 exec, exec, s[0:1]
	s_cmpk_lt_u32 s23, 0x80
	s_cselect_b64 s[2:3], -1, 0
	s_cmp_eq_u32 s24, 9
	s_cselect_b64 s[0:1], -1, 0
	s_and_b64 s[4:5], s[0:1], exec
	v_readlane_b32 s60, v252, 32
	v_readlane_b32 s4, v255, 1
	v_readlane_b32 s70, v252, 42
	v_readlane_b32 s71, v252, 43
	v_readlane_b32 s72, v252, 44
	v_readlane_b32 s73, v252, 45
	v_readlane_b32 s5, v255, 2
	s_cselect_b32 s24, s71, s73
	s_cselect_b32 s26, s70, s72
	s_lshl_b64 s[4:5], s[4:5], 2
	s_add_u32 s4, s26, s4
	v_lshlrev_b32_e32 v156, 3, v161
	s_addc_u32 s5, s24, s5
	s_add_i32 s24, 0, 0x20000
	v_or_b32_e32 v154, s14, v160
	v_or_b32_e32 v140, s18, v156
	v_readlane_b32 s61, v252, 33
	v_readlane_b32 s62, v252, 34
	v_readlane_b32 s63, v252, 35
	v_readlane_b32 s64, v252, 36
	v_readlane_b32 s65, v252, 37
	v_readlane_b32 s66, v252, 38
	v_readlane_b32 s67, v252, 39
	v_readlane_b32 s68, v252, 40
	v_readlane_b32 s69, v252, 41
	v_readlane_b32 s74, v252, 46
	v_readlane_b32 s75, v252, 47
	s_cmpk_gt_u32 s23, 0x7f
	s_waitcnt vmcnt(0) lgkmcnt(0)
	s_barrier
	v_add_u32_e32 v155, s22, v154
	v_lshlrev_b32_e32 v0, 7, v155
	v_readlane_b32 s60, v254, 45
	v_and_b32_e32 v0, 0x3e780, v0
	v_readlane_b32 s66, v254, 51
	v_readlane_b32 s67, v254, 52
	v_readlane_b32 s68, v254, 53
	v_readlane_b32 s69, v254, 54
	v_lshl_add_u64 v[132:133], s[66:67], 0, v[0:1]
	v_lshlrev_b32_e32 v134, 3, v154
	v_lshl_add_u64 v[130:131], s[68:69], 0, v[0:1]
	v_lshlrev_b32_e32 v182, 1, v140
	v_mov_b32_e32 v183, 0
	v_lshl_add_u64 v[184:185], v[132:133], 0, v[182:183]
	global_load_dwordx4 v[186:189], v[184:185], off
	v_lshl_add_u64 v[184:185], v[130:131], 0, v[182:183]
	global_load_dwordx4 v[190:193], v[184:185], off
	v_lshlrev_b32_e32 v0, 2, v140
	global_load_dwordx4 v[162:165], v0, s[4:5]
	global_load_dwordx4 v[168:171], v0, s[4:5]
	global_load_dwordx4 v[178:181], v0, s[4:5] offset:16
	v_lshlrev_b32_e32 v182, 1, v140
	v_mov_b32_e32 v183, 0
	v_or_b32_e32 v160, s13, v134
	v_bitop3_b32 v134, v134, 1, s13 bitop3:0x36
	v_lshl_add_u32 v157, v160, 2, s24
	v_lshl_add_u32 v134, v134, 2, s24
	ds_read_b32 v135, v157
	ds_read_b32 v134, v134
	v_readlane_b32 s61, v254, 46
	v_readlane_b32 s62, v254, 47
	v_readlane_b32 s63, v254, 48
	v_readlane_b32 s64, v254, 49
	s_waitcnt lgkmcnt(0)
	v_add_f32_e32 v134, v135, v134
	v_fmamk_f32 v134, v134, 0x3c800000, v236
	v_rsq_f32_e32 v136, v134
	v_readlane_b32 s65, v254, 50
	v_readlane_b32 s70, v254, 55
	v_readlane_b32 s71, v254, 56
	v_pk_mul_f32 v[126:127], v[126:127], v[136:137] op_sel_hi:[1,0]
	v_pk_mul_f32 v[128:129], v[128:129], v[136:137] op_sel_hi:[1,0]
	v_readlane_b32 s72, v254, 57
	v_readlane_b32 s73, v254, 58
	v_readlane_b32 s74, v254, 59
	v_readlane_b32 s75, v254, 60
	s_waitcnt vmcnt(0)
	v_pk_mul_f32 v[134:135], v[164:165], v[128:129]
	v_pk_mul_f32 v[128:129], v[162:163], v[126:127]
	s_cbranch_scc1 .LBB0_262
	v_lshlrev_b32_e32 v126, 1, v140
	v_mov_b32_e32 v127, v1
	v_lshl_add_u64 v[138:139], v[132:133], 0, v[126:127]
	v_lshl_add_u64 v[126:127], v[130:131], 0, v[126:127]
	v_mov_b64_e32 v[126:127], v[190:191]
	v_pk_mul_f32 v[162:163], v[128:129], v[126:127] op_sel:[1,0] op_sel_hi:[0,0]
	v_mov_b64_e32 v[138:139], v[186:187]
	v_pk_mul_f32 v[164:165], v[128:129], v[138:139]
	v_pk_fma_f32 v[128:129], v[128:129], v[138:139], v[162:163] op_sel_hi:[1,0,1]
	v_mov_b32_e32 v126, v139
	v_mul_f32_e32 v128, v135, v127
	v_pk_fma_f32 v[166:167], v[134:135], v[126:127], v[128:129] op_sel_hi:[1,1,0] neg_lo:[0,0,1] neg_hi:[0,0,1]
	v_mov_b32_e32 v138, v127
	v_mul_f32_e32 v126, v135, v139
	v_pk_fma_f32 v[126:127], v[134:135], v[138:139], v[126:127] op_sel_hi:[1,1,0]
	v_sub_f32_e32 v128, v164, v162
	v_mov_b32_e32 v134, v166
	v_mov_b32_e32 v135, v126
; template <int EPI>
; DI void gemm_epilogue(const Params& p, int layer, f32x4 (&acc)[2][2][4][2], int brow, int bcol, int pn, int wr, int wc,
;                       int fr, int fq, char* smem, int ksplit = -1) {
;     ...
;             u32x4 o;
; #pragma unroll
;             for (int n = 0; n < 2; ++n) {
;               const int cih = (wc & 1) * 32 + fq * 8 + n * 4;
;               f32x4 v = acc[ai][bj][m][n];
;               if (normed) {
;                 f32x4 g = *(const f32x4*)(gq + cih);
;                 v = v * rs * g;
;                 if (latent) {
;                   const float2 cs = *(const float2*)(p.ropec + spos * 32 + (cih >> 1));
;                   const float2 sn = *(const float2*)(p.ropes + spos * 32 + (cih >> 1));
;                   f32x4 r;
;                   r[0] = v[0] * cs.x - v[1] * sn.x;
;                   r[1] = v[0] * sn.x + v[1] * cs.x;
;                   r[2] = v[2] * cs.y - v[3] * sn.y;
;                   r[3] = v[2] * sn.y + v[3] * cs.y;
;                   v = r;
;                 }
;                 if (pn == 9) v = v * 0.125f;
;               }
;               o[2 * n] = pk_bf16(v[0], v[1]);
;               o[2 * n + 1] = pk_bf16(v[2], v[3]);
.LBB0_262:
	v_lshl_add_u64 v[126:127], s[4:5], 0, v[0:1]
	v_mov_b64_e32 v[162:163], v[178:179]
	v_mov_b64_e32 v[164:165], v[180:181]
	v_mov_b32_e32 v137, v136
	v_mov_b32_e32 v138, v136
	v_mov_b32_e32 v139, v136
	v_pk_mul_f32 v[124:125], v[124:125], v[138:139]
	v_pk_mul_f32 v[122:123], v[122:123], v[136:137]
	v_cndmask_b32_e64 v0, 0, 1, s[2:3]
	v_or_b32_e32 v141, 4, v140
	v_cmp_ne_u32_e64 s[40:41], 1, v0
	s_andn2_b64 vcc, exec, s[2:3]
	v_pk_mul_f32 v[138:139], v[124:125], v[164:165]
	v_pk_mul_f32 v[136:137], v[122:123], v[162:163]
	s_cbranch_vccnz .LBB0_264
	v_lshlrev_b32_e32 v0, 1, v141
	v_lshl_add_u64 v[122:123], v[132:133], 0, v[0:1]
	v_lshl_add_u64 v[124:125], v[130:131], 0, v[0:1]
	v_mov_b64_e32 v[122:123], v[188:189]
	v_pk_mul_f32 v[164:165], v[136:137], v[122:123]
	v_mov_b64_e32 v[124:125], v[192:193]
	v_pk_mul_f32 v[162:163], v[136:137], v[124:125] op_sel:[1,0] op_sel_hi:[0,0]
	v_mov_b32_e32 v124, v123
	v_mul_f32_e32 v0, v139, v125
	v_pk_fma_f32 v[136:137], v[136:137], v[122:123], v[162:163] op_sel_hi:[1,0,1]
	v_pk_fma_f32 v[166:167], v[138:139], v[124:125], v[0:1] op_sel_hi:[1,1,0] neg_lo:[0,0,1] neg_hi:[0,0,1]
	v_mov_b32_e32 v122, v125
	v_mul_f32_e32 v0, v139, v123
	v_pk_fma_f32 v[122:123], v[138:139], v[122:123], v[0:1] op_sel_hi:[1,1,0]
	v_sub_f32_e32 v136, v164, v162
	v_mov_b32_e32 v138, v166
	v_mov_b32_e32 v139, v122

; template <int EPI>
; DI void gemm_epilogue(const Params& p, int layer, f32x4 (&acc)[2][2][4][2], int brow, int bcol, int pn, int wr, int wc,
;                       int fr, int fq, char* smem, int ksplit = -1) {
;     ...
;             u32x4 o;
; #pragma unroll
;             for (int n = 0; n < 2; ++n) {
;               const int cih = (wc & 1) * 32 + fq * 8 + n * 4;
;               f32x4 v = acc[ai][bj][m][n];
;               if (normed) {
;                 f32x4 g = *(const f32x4*)(gq + cih);
;                 v = v * rs * g;
;                 if (latent) {
;                   const float2 cs = *(const float2*)(p.ropec + spos * 32 + (cih >> 1));
;                   const float2 sn = *(const float2*)(p.ropes + spos * 32 + (cih >> 1));
;                   f32x4 r;
;                   r[0] = v[0] * cs.x - v[1] * sn.x;
;                   r[1] = v[0] * sn.x + v[1] * cs.x;
;                   r[2] = v[2] * cs.y - v[3] * sn.y;
;                   r[3] = v[2] * sn.y + v[3] * cs.y;
;                   v = r;
;                 }
;                 if (pn == 9) v = v * 0.125f;
;               }
;               o[2 * n] = pk_bf16(v[0], v[1]);
;               o[2 * n + 1] = pk_bf16(v[2], v[3]);
.LBB0_268:
	v_mov_b64_e32 v[134:135], v[168:169]
	v_mov_b64_e32 v[136:137], v[170:171]
	v_mov_b32_e32 v138, v128
	v_mov_b32_e32 v139, v128
	v_pk_mul_f32 v[120:121], v[120:121], v[138:139]
	v_pk_mul_f32 v[118:119], v[118:119], v[128:129]
	s_and_b64 vcc, exec, s[40:41]
	v_pk_mul_f32 v[120:121], v[120:121], v[136:137]
	v_pk_mul_f32 v[118:119], v[118:119], v[134:135]
	s_cbranch_vccnz .LBB0_270
	v_lshlrev_b32_e32 v0, 1, v140
	v_lshl_add_u64 v[134:135], v[132:133], 0, v[0:1]
	v_lshl_add_u64 v[136:137], v[130:131], 0, v[0:1]
	v_mov_b64_e32 v[134:135], v[186:187]
	v_pk_mul_f32 v[156:157], v[118:119], v[134:135]
	v_mov_b64_e32 v[136:137], v[190:191]
	v_pk_mul_f32 v[138:139], v[118:119], v[136:137] op_sel:[1,0] op_sel_hi:[0,0]
	v_mov_b32_e32 v136, v135
	v_mul_f32_e32 v0, v121, v137
	v_pk_fma_f32 v[118:119], v[118:119], v[134:135], v[138:139] op_sel_hi:[1,0,1]
	v_pk_fma_f32 v[160:161], v[120:121], v[136:137], v[0:1] op_sel_hi:[1,1,0] neg_lo:[0,0,1] neg_hi:[0,0,1]
	v_mov_b32_e32 v134, v137
	v_mul_f32_e32 v0, v121, v135
	v_pk_fma_f32 v[134:135], v[120:121], v[134:135], v[0:1] op_sel_hi:[1,1,0]
	v_sub_f32_e32 v118, v156, v138
	v_mov_b32_e32 v120, v160
	v_mov_b32_e32 v121, v134

; template <int EPI>
; DI void gemm_epilogue(const Params& p, int layer, f32x4 (&acc)[2][2][4][2], int brow, int bcol, int pn, int wr, int wc,
;                       int fr, int fq, char* smem, int ksplit = -1) {
;     ...
;             u32x4 o;
; #pragma unroll
;             for (int n = 0; n < 2; ++n) {
;               const int cih = (wc & 1) * 32 + fq * 8 + n * 4;
;               f32x4 v = acc[ai][bj][m][n];
;               if (normed) {
;                 f32x4 g = *(const f32x4*)(gq + cih);
;                 v = v * rs * g;
;                 if (latent) {
;                   const float2 cs = *(const float2*)(p.ropec + spos * 32 + (cih >> 1));
;                   const float2 sn = *(const float2*)(p.ropes + spos * 32 + (cih >> 1));
;                   f32x4 r;
;                   r[0] = v[0] * cs.x - v[1] * sn.x;
;                   r[1] = v[0] * sn.x + v[1] * cs.x;
;                   r[2] = v[2] * cs.y - v[3] * sn.y;
;                   r[3] = v[2] * sn.y + v[3] * cs.y;
;                   v = r;
;                 }
;                 if (pn == 9) v = v * 0.125f;
;               }
;               o[2 * n] = pk_bf16(v[0], v[1]);
;               o[2 * n + 1] = pk_bf16(v[2], v[3]);
.LBB0_271:
	v_mov_b64_e32 v[134:135], v[178:179]
	v_mov_b64_e32 v[136:137], v[180:181]
	v_mov_b32_e32 v138, v128
	v_mov_b32_e32 v139, v128
	v_pk_mul_f32 v[114:115], v[114:115], v[128:129]
	v_pk_mul_f32 v[116:117], v[116:117], v[138:139]
	s_and_b64 vcc, exec, s[40:41]
	v_pk_mul_f32 v[116:117], v[116:117], v[136:137]
	v_pk_mul_f32 v[114:115], v[114:115], v[134:135]
	s_cbranch_vccnz .LBB0_273
	v_lshlrev_b32_e32 v0, 1, v141
	v_lshl_add_u64 v[128:129], v[132:133], 0, v[0:1]
	v_lshl_add_u64 v[130:131], v[130:131], 0, v[0:1]
	v_mov_b64_e32 v[128:129], v[188:189]
	v_pk_mul_f32 v[134:135], v[114:115], v[128:129]
	v_mov_b64_e32 v[130:131], v[192:193]
	v_pk_mul_f32 v[132:133], v[114:115], v[130:131] op_sel:[1,0] op_sel_hi:[0,0]
	v_mov_b32_e32 v130, v129
	v_mul_f32_e32 v0, v117, v131
	v_pk_fma_f32 v[114:115], v[114:115], v[128:129], v[132:133] op_sel_hi:[1,0,1]
	v_pk_fma_f32 v[136:137], v[116:117], v[130:131], v[0:1] op_sel_hi:[1,1,0] neg_lo:[0,0,1] neg_hi:[0,0,1]
	v_mov_b32_e32 v128, v131
	v_mul_f32_e32 v0, v117, v129
	v_pk_fma_f32 v[128:129], v[116:117], v[128:129], v[0:1] op_sel_hi:[1,1,0]
	v_sub_f32_e32 v114, v134, v132
	v_mov_b32_e32 v116, v136
	v_mov_b32_e32 v117, v128

; template <int EPI>
; DI void gemm_epilogue(const Params& p, int layer, f32x4 (&acc)[2][2][4][2], int brow, int bcol, int pn, int wr, int wc,
;                       int fr, int fq, char* smem, int ksplit = -1) {
;     ...
;           const int rl = ai * 128 + wr * 64 + m * 16 + fr;
;           const int row = brow + rl;
;           const int spos = row & (SEQ - 1);
; #pragma unroll
;           for (int bj = 0; bj < 2; ++bj) {
;             const bool normed = (pn == 9) || (bj == 0);
;             float rs = 1.f;
;             if (normed) {
;               float tot = xch[rl * 8 + bj * 4 + wc] + xch[rl * 8 + bj * 4 + (wc ^ 1)];
;               rs = __builtin_amdgcn_rsqf(tot * (1.f / 64.f) + EPSN);
;             }
;             u32x4 o;
; #pragma unroll
;             for (int n = 0; n < 2; ++n) {
;               const int cih = (wc & 1) * 32 + fq * 8 + n * 4;
;               f32x4 v = acc[ai][bj][m][n];
;               if (normed) {
;                 f32x4 g = *(const f32x4*)(gq + cih);
;                 v = v * rs * g;
;                 if (latent) {
;                   const float2 cs = *(const float2*)(p.ropec + spos * 32 + (cih >> 1));
;                   const float2 sn = *(const float2*)(p.ropes + spos * 32 + (cih >> 1));
;                   f32x4 r;
;                   r[0] = v[0] * cs.x - v[1] * sn.x;
;                   r[1] = v[0] * sn.x + v[1] * cs.x;
;                   r[2] = v[2] * cs.y - v[3] * sn.y;
;                   r[3] = v[2] * sn.y + v[3] * cs.y;
;                   v = r;
;                 }
;                 if (pn == 9) v = v * 0.125f;
;               }
;               o[2 * n] = pk_bf16(v[0], v[1]);
;               o[2 * n + 1] = pk_bf16(v[2], v[3]);
;             }
;             *(u32x4*)(Z + (size_t)row * ZW + bcol + bj * 128 + wc * 32 + fq * 8) = o;
.LBB0_274:
	v_cvt_pk_bf16_f32 v118, v118, v119
	v_cvt_pk_bf16_f32 v119, v120, v121
	v_cvt_pk_bf16_f32 v120, v114, v115
	v_cvt_pk_bf16_f32 v121, v116, v117
	global_store_dwordx4 v[124:125], v[118:121], off offset:256
	v_mov_b64_e32 v[128:129], v[168:169]
	v_mov_b64_e32 v[130:131], v[170:171]
	v_or_b32_e32 v0, 16, v154
	v_lshlrev_b32_e32 v114, 3, v0
	v_or_b32_e32 v121, s13, v114
	v_bitop3_b32 v114, v114, 1, s13 bitop3:0x36
	v_lshl_add_u32 v120, v121, 2, s24
	v_lshl_add_u32 v114, v114, 2, s24
	ds_read_b32 v115, v120
	ds_read_b32 v114, v114
	v_add_u32_e32 v124, s22, v0
	v_lshlrev_b32_e32 v0, 7, v124
	v_readlane_b32 s60, v254, 45
	v_and_b32_e32 v0, 0x3ef80, v0
	s_waitcnt lgkmcnt(0)
	v_add_f32_e32 v114, v115, v114
	v_fmamk_f32 v114, v114, 0x3c800000, v236
	v_rsq_f32_e32 v118, v114
	v_readlane_b32 s66, v254, 51
	v_readlane_b32 s67, v254, 52
	v_readlane_b32 s68, v254, 53
	v_readlane_b32 s69, v254, 54
	v_pk_mul_f32 v[110:111], v[110:111], v[118:119] op_sel_hi:[1,0]
	v_pk_mul_f32 v[112:113], v[112:113], v[118:119] op_sel_hi:[1,0]
	s_and_b64 vcc, exec, s[40:41]
	v_lshl_add_u64 v[116:117], s[66:67], 0, v[0:1]
	v_lshl_add_u64 v[114:115], s[68:69], 0, v[0:1]
	v_lshl_add_u64 v[184:185], v[116:117], 0, v[182:183]
	global_load_dwordx4 v[186:189], v[184:185], off
	v_lshl_add_u64 v[184:185], v[114:115], 0, v[182:183]
	global_load_dwordx4 v[190:193], v[184:185], off
	v_readlane_b32 s61, v254, 46
	v_readlane_b32 s62, v254, 47
	v_readlane_b32 s63, v254, 48
	v_readlane_b32 s64, v254, 49
	v_readlane_b32 s65, v254, 50
	v_readlane_b32 s70, v254, 55
	v_readlane_b32 s71, v254, 56
	v_readlane_b32 s72, v254, 57
	v_readlane_b32 s73, v254, 58
	v_readlane_b32 s74, v254, 59
	v_readlane_b32 s75, v254, 60
	v_pk_mul_f32 v[112:113], v[130:131], v[112:113]
	v_pk_mul_f32 v[110:111], v[128:129], v[110:111]
	s_cbranch_vccnz .LBB0_276
	v_lshlrev_b32_e32 v0, 1, v140
	v_lshl_add_u64 v[128:129], v[116:117], 0, v[0:1]
	v_lshl_add_u64 v[130:131], v[114:115], 0, v[0:1]
	s_waitcnt vmcnt(0)
	v_mov_b64_e32 v[128:129], v[186:187]
	v_pk_mul_f32 v[134:135], v[110:111], v[128:129]
	v_mov_b64_e32 v[130:131], v[190:191]
	v_pk_mul_f32 v[132:133], v[110:111], v[130:131] op_sel:[1,0] op_sel_hi:[0,0]
	v_mov_b32_e32 v130, v129
	v_mul_f32_e32 v0, v113, v131
	v_pk_fma_f32 v[110:111], v[110:111], v[128:129], v[132:133] op_sel_hi:[1,0,1]
	v_pk_fma_f32 v[136:137], v[112:113], v[130:131], v[0:1] op_sel_hi:[1,1,0] neg_lo:[0,0,1] neg_hi:[0,0,1]
	v_mov_b32_e32 v128, v131
	v_mul_f32_e32 v0, v113, v129
	v_pk_fma_f32 v[128:129], v[112:113], v[128:129], v[0:1] op_sel_hi:[1,1,0]
	v_sub_f32_e32 v110, v134, v132
	v_mov_b32_e32 v112, v136
	v_mov_b32_e32 v113, v128
.LBB0_276:
	v_mov_b64_e32 v[128:129], v[178:179]
	v_mov_b64_e32 v[130:131], v[180:181]
	v_mov_b32_e32 v119, v118
	v_mov_b32_e32 v132, v118
	v_mov_b32_e32 v133, v118
	v_pk_mul_f32 v[108:109], v[108:109], v[132:133]
	v_pk_mul_f32 v[106:107], v[106:107], v[118:119]
	s_and_b64 vcc, exec, s[40:41]
	v_pk_mul_f32 v[118:119], v[108:109], v[130:131]
	v_pk_mul_f32 v[108:109], v[106:107], v[128:129]
	s_cbranch_vccnz .LBB0_278
	v_lshlrev_b32_e32 v0, 1, v141
	v_lshl_add_u64 v[106:107], v[116:117], 0, v[0:1]
	v_lshl_add_u64 v[128:129], v[114:115], 0, v[0:1]
	v_mov_b64_e32 v[106:107], v[188:189]
	v_pk_mul_f32 v[132:133], v[108:109], v[106:107]
	v_mov_b64_e32 v[128:129], v[192:193]
	v_pk_mul_f32 v[130:131], v[108:109], v[128:129] op_sel:[1,0] op_sel_hi:[0,0]
	v_mov_b32_e32 v128, v107
	v_mul_f32_e32 v0, v119, v129
	v_pk_fma_f32 v[108:109], v[108:109], v[106:107], v[130:131] op_sel_hi:[1,0,1]
	v_pk_fma_f32 v[134:135], v[118:119], v[128:129], v[0:1] op_sel_hi:[1,1,0] neg_lo:[0,0,1] neg_hi:[0,0,1]
	v_mov_b32_e32 v106, v129
	v_mul_f32_e32 v0, v119, v107
	v_pk_fma_f32 v[106:107], v[118:119], v[106:107], v[0:1] op_sel_hi:[1,1,0]
	v_sub_f32_e32 v108, v132, v130
	v_mov_b32_e32 v118, v134
	v_mov_b32_e32 v119, v106

; template <int EPI>
; DI void gemm_epilogue(const Params& p, int layer, f32x4 (&acc)[2][2][4][2], int brow, int bcol, int pn, int wr, int wc,
;                       int fr, int fq, char* smem, int ksplit = -1) {
;     ...
;             u32x4 o;
; #pragma unroll
;             for (int n = 0; n < 2; ++n) {
;               const int cih = (wc & 1) * 32 + fq * 8 + n * 4;
;               f32x4 v = acc[ai][bj][m][n];
;               if (normed) {
;                 f32x4 g = *(const f32x4*)(gq + cih);
;                 v = v * rs * g;
;                 if (latent) {
;                   const float2 cs = *(const float2*)(p.ropec + spos * 32 + (cih >> 1));
;                   const float2 sn = *(const float2*)(p.ropes + spos * 32 + (cih >> 1));
;                   f32x4 r;
;                   r[0] = v[0] * cs.x - v[1] * sn.x;
;                   r[1] = v[0] * sn.x + v[1] * cs.x;
;                   r[2] = v[2] * cs.y - v[3] * sn.y;
;                   r[3] = v[2] * sn.y + v[3] * cs.y;
;                   v = r;
;                 }
;                 if (pn == 9) v = v * 0.125f;
;               }
;               o[2 * n] = pk_bf16(v[0], v[1]);
;               o[2 * n + 1] = pk_bf16(v[2], v[3]);
.LBB0_282:
	v_mov_b64_e32 v[110:111], v[168:169]
	v_mov_b64_e32 v[112:113], v[170:171]
	v_mov_b32_e32 v118, v108
	v_mov_b32_e32 v119, v108
	v_pk_mul_f32 v[104:105], v[104:105], v[118:119]
	v_pk_mul_f32 v[102:103], v[102:103], v[108:109]
	s_and_b64 vcc, exec, s[40:41]
	v_pk_mul_f32 v[104:105], v[104:105], v[112:113]
	v_pk_mul_f32 v[102:103], v[102:103], v[110:111]
	s_cbranch_vccnz .LBB0_284
	v_lshlrev_b32_e32 v0, 1, v140
	v_lshl_add_u64 v[110:111], v[116:117], 0, v[0:1]
	v_lshl_add_u64 v[112:113], v[114:115], 0, v[0:1]
	v_mov_b64_e32 v[110:111], v[186:187]
	v_pk_mul_f32 v[120:121], v[102:103], v[110:111]
	v_mov_b64_e32 v[112:113], v[190:191]
	v_pk_mul_f32 v[118:119], v[102:103], v[112:113] op_sel:[1,0] op_sel_hi:[0,0]
	v_mov_b32_e32 v112, v111
	v_mul_f32_e32 v0, v105, v113
	v_pk_fma_f32 v[102:103], v[102:103], v[110:111], v[118:119] op_sel_hi:[1,0,1]
	v_pk_fma_f32 v[124:125], v[104:105], v[112:113], v[0:1] op_sel_hi:[1,1,0] neg_lo:[0,0,1] neg_hi:[0,0,1]
	v_mov_b32_e32 v110, v113
	v_mul_f32_e32 v0, v105, v111
	v_pk_fma_f32 v[110:111], v[104:105], v[110:111], v[0:1] op_sel_hi:[1,1,0]
	v_sub_f32_e32 v102, v120, v118
	v_mov_b32_e32 v104, v124
	v_mov_b32_e32 v105, v110

; template <int EPI>
; DI void gemm_epilogue(const Params& p, int layer, f32x4 (&acc)[2][2][4][2], int brow, int bcol, int pn, int wr, int wc,
;                       int fr, int fq, char* smem, int ksplit = -1) {
;     ...
;             u32x4 o;
; #pragma unroll
;             for (int n = 0; n < 2; ++n) {
;               const int cih = (wc & 1) * 32 + fq * 8 + n * 4;
;               f32x4 v = acc[ai][bj][m][n];
;               if (normed) {
;                 f32x4 g = *(const f32x4*)(gq + cih);
;                 v = v * rs * g;
;                 if (latent) {
;                   const float2 cs = *(const float2*)(p.ropec + spos * 32 + (cih >> 1));
;                   const float2 sn = *(const float2*)(p.ropes + spos * 32 + (cih >> 1));
;                   f32x4 r;
;                   r[0] = v[0] * cs.x - v[1] * sn.x;
;                   r[1] = v[0] * sn.x + v[1] * cs.x;
;                   r[2] = v[2] * cs.y - v[3] * sn.y;
;                   r[3] = v[2] * sn.y + v[3] * cs.y;
;                   v = r;
;                 }
;                 if (pn == 9) v = v * 0.125f;
;               }
;               o[2 * n] = pk_bf16(v[0], v[1]);
;               o[2 * n + 1] = pk_bf16(v[2], v[3]);
.LBB0_285:
	v_mov_b64_e32 v[110:111], v[178:179]
	v_mov_b64_e32 v[112:113], v[180:181]
	v_mov_b32_e32 v118, v108
	v_mov_b32_e32 v119, v108
	v_pk_mul_f32 v[98:99], v[98:99], v[108:109]
	v_pk_mul_f32 v[100:101], v[100:101], v[118:119]
	s_and_b64 vcc, exec, s[40:41]
	v_pk_mul_f32 v[100:101], v[100:101], v[112:113]
	v_pk_mul_f32 v[98:99], v[98:99], v[110:111]
	s_cbranch_vccnz .LBB0_287
	v_lshlrev_b32_e32 v0, 1, v141
	v_lshl_add_u64 v[108:109], v[116:117], 0, v[0:1]
	v_lshl_add_u64 v[110:111], v[114:115], 0, v[0:1]
	v_mov_b64_e32 v[108:109], v[188:189]
	v_pk_mul_f32 v[114:115], v[98:99], v[108:109]
	v_mov_b64_e32 v[110:111], v[192:193]
	v_pk_mul_f32 v[112:113], v[98:99], v[110:111] op_sel:[1,0] op_sel_hi:[0,0]
	v_mov_b32_e32 v110, v109
	v_mul_f32_e32 v0, v101, v111
	v_pk_fma_f32 v[98:99], v[98:99], v[108:109], v[112:113] op_sel_hi:[1,0,1]
	v_pk_fma_f32 v[116:117], v[100:101], v[110:111], v[0:1] op_sel_hi:[1,1,0] neg_lo:[0,0,1] neg_hi:[0,0,1]
	v_mov_b32_e32 v108, v111
	v_mul_f32_e32 v0, v101, v109
	v_pk_fma_f32 v[108:109], v[100:101], v[108:109], v[0:1] op_sel_hi:[1,1,0]
	v_sub_f32_e32 v98, v114, v112
	v_mov_b32_e32 v100, v116
	v_mov_b32_e32 v101, v108

; template <int EPI>
; DI void gemm_epilogue(const Params& p, int layer, f32x4 (&acc)[2][2][4][2], int brow, int bcol, int pn, int wr, int wc,
;                       int fr, int fq, char* smem, int ksplit = -1) {
;     ...
;           const int rl = ai * 128 + wr * 64 + m * 16 + fr;
;           const int row = brow + rl;
;           const int spos = row & (SEQ - 1);
; #pragma unroll
;           for (int bj = 0; bj < 2; ++bj) {
;             const bool normed = (pn == 9) || (bj == 0);
;             float rs = 1.f;
;             if (normed) {
;               float tot = xch[rl * 8 + bj * 4 + wc] + xch[rl * 8 + bj * 4 + (wc ^ 1)];
;               rs = __builtin_amdgcn_rsqf(tot * (1.f / 64.f) + EPSN);
;             }
;             u32x4 o;
; #pragma unroll
;             for (int n = 0; n < 2; ++n) {
;               const int cih = (wc & 1) * 32 + fq * 8 + n * 4;
;               f32x4 v = acc[ai][bj][m][n];
;               if (normed) {
;                 f32x4 g = *(const f32x4*)(gq + cih);
;                 v = v * rs * g;
;                 if (latent) {
;                   const float2 cs = *(const float2*)(p.ropec + spos * 32 + (cih >> 1));
;                   const float2 sn = *(const float2*)(p.ropes + spos * 32 + (cih >> 1));
;                   f32x4 r;
;                   r[0] = v[0] * cs.x - v[1] * sn.x;
;                   r[1] = v[0] * sn.x + v[1] * cs.x;
;                   r[2] = v[2] * cs.y - v[3] * sn.y;
;                   r[3] = v[2] * sn.y + v[3] * cs.y;
;                   v = r;
;                 }
;                 if (pn == 9) v = v * 0.125f;
;               }
;               o[2 * n] = pk_bf16(v[0], v[1]);
;               o[2 * n + 1] = pk_bf16(v[2], v[3]);
;             }
;             *(u32x4*)(Z + (size_t)row * ZW + bcol + bj * 128 + wc * 32 + fq * 8) = o;
.LBB0_288:
	v_cvt_pk_bf16_f32 v102, v102, v103
	v_cvt_pk_bf16_f32 v103, v104, v105
	v_cvt_pk_bf16_f32 v104, v98, v99
	v_cvt_pk_bf16_f32 v105, v100, v101
	global_store_dwordx4 v[106:107], v[102:105], off offset:256
	v_mov_b64_e32 v[108:109], v[168:169]
	v_mov_b64_e32 v[110:111], v[170:171]
	v_or_b32_e32 v0, 32, v154
	v_lshlrev_b32_e32 v98, 3, v0
	v_or_b32_e32 v105, s13, v98
	v_bitop3_b32 v98, v98, 1, s13 bitop3:0x36
	v_lshl_add_u32 v104, v105, 2, s24
	v_lshl_add_u32 v98, v98, 2, s24
	ds_read_b32 v99, v104
	ds_read_b32 v98, v98
	v_add_u32_e32 v106, s22, v0
	v_lshlrev_b32_e32 v0, 7, v106
	v_readlane_b32 s60, v254, 45
	v_and_b32_e32 v0, 0x3f780, v0
	s_waitcnt lgkmcnt(0)
	v_add_f32_e32 v98, v99, v98
	v_fmamk_f32 v98, v98, 0x3c800000, v236
	v_rsq_f32_e32 v102, v98
	v_readlane_b32 s66, v254, 51
	v_readlane_b32 s67, v254, 52
	v_readlane_b32 s68, v254, 53
	v_readlane_b32 s69, v254, 54
	v_pk_mul_f32 v[94:95], v[94:95], v[102:103] op_sel_hi:[1,0]
	v_pk_mul_f32 v[96:97], v[96:97], v[102:103] op_sel_hi:[1,0]
	s_and_b64 vcc, exec, s[40:41]
	v_lshl_add_u64 v[100:101], s[66:67], 0, v[0:1]
	v_lshl_add_u64 v[98:99], s[68:69], 0, v[0:1]
	v_lshl_add_u64 v[184:185], v[100:101], 0, v[182:183]
	global_load_dwordx4 v[186:189], v[184:185], off
	v_lshl_add_u64 v[184:185], v[98:99], 0, v[182:183]
	global_load_dwordx4 v[190:193], v[184:185], off
	v_readlane_b32 s61, v254, 46
	v_readlane_b32 s62, v254, 47
	v_readlane_b32 s63, v254, 48
	v_readlane_b32 s64, v254, 49
	v_readlane_b32 s65, v254, 50
	v_readlane_b32 s70, v254, 55
	v_readlane_b32 s71, v254, 56
	v_readlane_b32 s72, v254, 57
	v_readlane_b32 s73, v254, 58
	v_readlane_b32 s74, v254, 59
	v_readlane_b32 s75, v254, 60
	v_pk_mul_f32 v[96:97], v[110:111], v[96:97]
	v_pk_mul_f32 v[94:95], v[108:109], v[94:95]
	s_cbranch_vccnz .LBB0_290
	v_lshlrev_b32_e32 v0, 1, v140
	v_lshl_add_u64 v[108:109], v[100:101], 0, v[0:1]
	v_lshl_add_u64 v[110:111], v[98:99], 0, v[0:1]
	s_waitcnt vmcnt(0)
	v_mov_b64_e32 v[108:109], v[186:187]
	v_pk_mul_f32 v[114:115], v[94:95], v[108:109]
	v_mov_b64_e32 v[110:111], v[190:191]
	v_pk_mul_f32 v[112:113], v[94:95], v[110:111] op_sel:[1,0] op_sel_hi:[0,0]
	v_mov_b32_e32 v110, v109
	v_mul_f32_e32 v0, v97, v111
	v_pk_fma_f32 v[94:95], v[94:95], v[108:109], v[112:113] op_sel_hi:[1,0,1]
	v_pk_fma_f32 v[116:117], v[96:97], v[110:111], v[0:1] op_sel_hi:[1,1,0] neg_lo:[0,0,1] neg_hi:[0,0,1]
	v_mov_b32_e32 v108, v111
	v_mul_f32_e32 v0, v97, v109
	v_pk_fma_f32 v[108:109], v[96:97], v[108:109], v[0:1] op_sel_hi:[1,1,0]
	v_sub_f32_e32 v94, v114, v112
	v_mov_b32_e32 v96, v116
	v_mov_b32_e32 v97, v108
.LBB0_290:
	v_mov_b64_e32 v[108:109], v[178:179]
	v_mov_b64_e32 v[110:111], v[180:181]
	v_mov_b32_e32 v103, v102
	v_mov_b32_e32 v112, v102
	v_mov_b32_e32 v113, v102
	v_pk_mul_f32 v[92:93], v[92:93], v[112:113]
	v_pk_mul_f32 v[90:91], v[90:91], v[102:103]
	s_and_b64 vcc, exec, s[40:41]
	v_pk_mul_f32 v[102:103], v[92:93], v[110:111]
	v_pk_mul_f32 v[92:93], v[90:91], v[108:109]
	s_cbranch_vccnz .LBB0_292
	v_lshlrev_b32_e32 v0, 1, v141
	v_lshl_add_u64 v[90:91], v[100:101], 0, v[0:1]
	v_lshl_add_u64 v[108:109], v[98:99], 0, v[0:1]
	v_mov_b64_e32 v[90:91], v[188:189]
	v_pk_mul_f32 v[112:113], v[92:93], v[90:91]
	v_mov_b64_e32 v[108:109], v[192:193]
	v_pk_mul_f32 v[110:111], v[92:93], v[108:109] op_sel:[1,0] op_sel_hi:[0,0]
	v_mov_b32_e32 v108, v91
	v_mul_f32_e32 v0, v103, v109
	v_pk_fma_f32 v[92:93], v[92:93], v[90:91], v[110:111] op_sel_hi:[1,0,1]
	v_pk_fma_f32 v[114:115], v[102:103], v[108:109], v[0:1] op_sel_hi:[1,1,0] neg_lo:[0,0,1] neg_hi:[0,0,1]
	v_mov_b32_e32 v90, v109
	v_mul_f32_e32 v0, v103, v91
	v_pk_fma_f32 v[90:91], v[102:103], v[90:91], v[0:1] op_sel_hi:[1,1,0]
	v_sub_f32_e32 v92, v112, v110
	v_mov_b32_e32 v102, v114
	v_mov_b32_e32 v103, v90

; template <int EPI>
; DI void gemm_epilogue(const Params& p, int layer, f32x4 (&acc)[2][2][4][2], int brow, int bcol, int pn, int wr, int wc,
;                       int fr, int fq, char* smem, int ksplit = -1) {
;     ...
;             u32x4 o;
; #pragma unroll
;             for (int n = 0; n < 2; ++n) {
;               const int cih = (wc & 1) * 32 + fq * 8 + n * 4;
;               f32x4 v = acc[ai][bj][m][n];
;               if (normed) {
;                 f32x4 g = *(const f32x4*)(gq + cih);
;                 v = v * rs * g;
;                 if (latent) {
;                   const float2 cs = *(const float2*)(p.ropec + spos * 32 + (cih >> 1));
;                   const float2 sn = *(const float2*)(p.ropes + spos * 32 + (cih >> 1));
;                   f32x4 r;
;                   r[0] = v[0] * cs.x - v[1] * sn.x;
;                   r[1] = v[0] * sn.x + v[1] * cs.x;
;                   r[2] = v[2] * cs.y - v[3] * sn.y;
;                   r[3] = v[2] * sn.y + v[3] * cs.y;
;                   v = r;
;                 }
;                 if (pn == 9) v = v * 0.125f;
;               }
;               o[2 * n] = pk_bf16(v[0], v[1]);
;               o[2 * n + 1] = pk_bf16(v[2], v[3]);
.LBB0_296:
	v_mov_b64_e32 v[94:95], v[168:169]
	v_mov_b64_e32 v[96:97], v[170:171]
	v_mov_b32_e32 v102, v92
	v_mov_b32_e32 v103, v92
	v_pk_mul_f32 v[88:89], v[88:89], v[102:103]
	v_pk_mul_f32 v[86:87], v[86:87], v[92:93]
	s_and_b64 vcc, exec, s[40:41]
	v_pk_mul_f32 v[88:89], v[88:89], v[96:97]
	v_pk_mul_f32 v[86:87], v[86:87], v[94:95]
	s_cbranch_vccnz .LBB0_298
	v_lshlrev_b32_e32 v0, 1, v140
	v_lshl_add_u64 v[94:95], v[100:101], 0, v[0:1]
	v_lshl_add_u64 v[96:97], v[98:99], 0, v[0:1]
	v_mov_b64_e32 v[94:95], v[186:187]
	v_pk_mul_f32 v[104:105], v[86:87], v[94:95]
	v_mov_b64_e32 v[96:97], v[190:191]
	v_pk_mul_f32 v[102:103], v[86:87], v[96:97] op_sel:[1,0] op_sel_hi:[0,0]
	v_mov_b32_e32 v96, v95
	v_mul_f32_e32 v0, v89, v97
	v_pk_fma_f32 v[86:87], v[86:87], v[94:95], v[102:103] op_sel_hi:[1,0,1]
	v_pk_fma_f32 v[106:107], v[88:89], v[96:97], v[0:1] op_sel_hi:[1,1,0] neg_lo:[0,0,1] neg_hi:[0,0,1]
	v_mov_b32_e32 v94, v97
	v_mul_f32_e32 v0, v89, v95
	v_pk_fma_f32 v[94:95], v[88:89], v[94:95], v[0:1] op_sel_hi:[1,1,0]
	v_sub_f32_e32 v86, v104, v102
	v_mov_b32_e32 v88, v106
	v_mov_b32_e32 v89, v94

; template <int EPI>
; DI void gemm_epilogue(const Params& p, int layer, f32x4 (&acc)[2][2][4][2], int brow, int bcol, int pn, int wr, int wc,
;                       int fr, int fq, char* smem, int ksplit = -1) {
;     ...
;             u32x4 o;
; #pragma unroll
;             for (int n = 0; n < 2; ++n) {
;               const int cih = (wc & 1) * 32 + fq * 8 + n * 4;
;               f32x4 v = acc[ai][bj][m][n];
;               if (normed) {
;                 f32x4 g = *(const f32x4*)(gq + cih);
;                 v = v * rs * g;
;                 if (latent) {
;                   const float2 cs = *(const float2*)(p.ropec + spos * 32 + (cih >> 1));
;                   const float2 sn = *(const float2*)(p.ropes + spos * 32 + (cih >> 1));
;                   f32x4 r;
;                   r[0] = v[0] * cs.x - v[1] * sn.x;
;                   r[1] = v[0] * sn.x + v[1] * cs.x;
;                   r[2] = v[2] * cs.y - v[3] * sn.y;
;                   r[3] = v[2] * sn.y + v[3] * cs.y;
;                   v = r;
;                 }
;                 if (pn == 9) v = v * 0.125f;
;               }
;               o[2 * n] = pk_bf16(v[0], v[1]);
;               o[2 * n + 1] = pk_bf16(v[2], v[3]);
.LBB0_299:
	v_mov_b64_e32 v[94:95], v[178:179]
	v_mov_b64_e32 v[96:97], v[180:181]
	v_mov_b32_e32 v102, v92
	v_mov_b32_e32 v103, v92
	v_pk_mul_f32 v[82:83], v[82:83], v[92:93]
	v_pk_mul_f32 v[84:85], v[84:85], v[102:103]
	s_and_b64 vcc, exec, s[40:41]
	v_pk_mul_f32 v[84:85], v[84:85], v[96:97]
	v_pk_mul_f32 v[82:83], v[82:83], v[94:95]
	s_cbranch_vccnz .LBB0_301
	v_lshlrev_b32_e32 v0, 1, v141
	v_lshl_add_u64 v[92:93], v[100:101], 0, v[0:1]
	v_lshl_add_u64 v[94:95], v[98:99], 0, v[0:1]
	v_mov_b64_e32 v[92:93], v[188:189]
	v_pk_mul_f32 v[98:99], v[82:83], v[92:93]
	v_mov_b64_e32 v[94:95], v[192:193]
	v_pk_mul_f32 v[96:97], v[82:83], v[94:95] op_sel:[1,0] op_sel_hi:[0,0]
	v_mov_b32_e32 v94, v93
	v_mul_f32_e32 v0, v85, v95
	v_pk_fma_f32 v[82:83], v[82:83], v[92:93], v[96:97] op_sel_hi:[1,0,1]
	v_pk_fma_f32 v[100:101], v[84:85], v[94:95], v[0:1] op_sel_hi:[1,1,0] neg_lo:[0,0,1] neg_hi:[0,0,1]
	v_mov_b32_e32 v92, v95
	v_mul_f32_e32 v0, v85, v93
	v_pk_fma_f32 v[92:93], v[84:85], v[92:93], v[0:1] op_sel_hi:[1,1,0]
	v_sub_f32_e32 v82, v98, v96
	v_mov_b32_e32 v84, v100
	v_mov_b32_e32 v85, v92

; template <int EPI>
; DI void gemm_epilogue(const Params& p, int layer, f32x4 (&acc)[2][2][4][2], int brow, int bcol, int pn, int wr, int wc,
;                       int fr, int fq, char* smem, int ksplit = -1) {
;     ...
;           const int rl = ai * 128 + wr * 64 + m * 16 + fr;
;           const int row = brow + rl;
;           const int spos = row & (SEQ - 1);
; #pragma unroll
;           for (int bj = 0; bj < 2; ++bj) {
;             const bool normed = (pn == 9) || (bj == 0);
;             float rs = 1.f;
;             if (normed) {
;               float tot = xch[rl * 8 + bj * 4 + wc] + xch[rl * 8 + bj * 4 + (wc ^ 1)];
;               rs = __builtin_amdgcn_rsqf(tot * (1.f / 64.f) + EPSN);
;             }
;             u32x4 o;
; #pragma unroll
;             for (int n = 0; n < 2; ++n) {
;               const int cih = (wc & 1) * 32 + fq * 8 + n * 4;
;               f32x4 v = acc[ai][bj][m][n];
;               if (normed) {
;                 f32x4 g = *(const f32x4*)(gq + cih);
;                 v = v * rs * g;
;                 if (latent) {
;                   const float2 cs = *(const float2*)(p.ropec + spos * 32 + (cih >> 1));
;                   const float2 sn = *(const float2*)(p.ropes + spos * 32 + (cih >> 1));
;                   f32x4 r;
;                   r[0] = v[0] * cs.x - v[1] * sn.x;
;                   r[1] = v[0] * sn.x + v[1] * cs.x;
;                   r[2] = v[2] * cs.y - v[3] * sn.y;
;                   r[3] = v[2] * sn.y + v[3] * cs.y;
;                   v = r;
;                 }
;                 if (pn == 9) v = v * 0.125f;
;               }
;               o[2 * n] = pk_bf16(v[0], v[1]);
;               o[2 * n + 1] = pk_bf16(v[2], v[3]);
;             }
;             *(u32x4*)(Z + (size_t)row * ZW + bcol + bj * 128 + wc * 32 + fq * 8) = o;
.LBB0_302:
	v_cvt_pk_bf16_f32 v86, v86, v87
	v_cvt_pk_bf16_f32 v87, v88, v89
	v_cvt_pk_bf16_f32 v88, v82, v83
	v_cvt_pk_bf16_f32 v89, v84, v85
	global_store_dwordx4 v[90:91], v[86:89], off offset:256
	v_mov_b64_e32 v[92:93], v[168:169]
	v_mov_b64_e32 v[94:95], v[170:171]
	v_or_b32_e32 v0, 48, v154
	v_lshlrev_b32_e32 v82, 3, v0
	v_or_b32_e32 v89, s13, v82
	v_bitop3_b32 v82, v82, 1, s13 bitop3:0x36
	v_lshl_add_u32 v88, v89, 2, s24
	v_lshl_add_u32 v82, v82, 2, s24
	ds_read_b32 v83, v88
	ds_read_b32 v82, v82
	v_add_u32_e32 v90, s22, v0
	v_lshlrev_b32_e32 v0, 7, v90
	v_readlane_b32 s60, v254, 45
	v_and_b32_e32 v0, 0x3ff80, v0
	s_waitcnt lgkmcnt(0)
	v_add_f32_e32 v82, v83, v82
	v_fmamk_f32 v82, v82, 0x3c800000, v236
	v_rsq_f32_e32 v86, v82
	v_readlane_b32 s66, v254, 51
	v_readlane_b32 s67, v254, 52
	v_readlane_b32 s68, v254, 53
	v_readlane_b32 s69, v254, 54
	v_pk_mul_f32 v[78:79], v[78:79], v[86:87] op_sel_hi:[1,0]
	v_pk_mul_f32 v[80:81], v[80:81], v[86:87] op_sel_hi:[1,0]
	s_and_b64 vcc, exec, s[40:41]
	v_lshl_add_u64 v[84:85], s[66:67], 0, v[0:1]
	v_lshl_add_u64 v[82:83], s[68:69], 0, v[0:1]
	v_lshl_add_u64 v[184:185], v[84:85], 0, v[182:183]
	global_load_dwordx4 v[186:189], v[184:185], off
	v_lshl_add_u64 v[184:185], v[82:83], 0, v[182:183]
	global_load_dwordx4 v[190:193], v[184:185], off
	v_readlane_b32 s61, v254, 46
	v_readlane_b32 s62, v254, 47
	v_readlane_b32 s63, v254, 48
	v_readlane_b32 s64, v254, 49
	v_readlane_b32 s65, v254, 50
	v_readlane_b32 s70, v254, 55
	v_readlane_b32 s71, v254, 56
	v_readlane_b32 s72, v254, 57
	v_readlane_b32 s73, v254, 58
	v_readlane_b32 s74, v254, 59
	v_readlane_b32 s75, v254, 60
	v_pk_mul_f32 v[80:81], v[94:95], v[80:81]
	v_pk_mul_f32 v[78:79], v[92:93], v[78:79]
	s_cbranch_vccnz .LBB0_304
	v_lshlrev_b32_e32 v0, 1, v140
	v_lshl_add_u64 v[92:93], v[84:85], 0, v[0:1]
	v_lshl_add_u64 v[94:95], v[82:83], 0, v[0:1]
	s_waitcnt vmcnt(0)
	v_mov_b64_e32 v[92:93], v[186:187]
	v_pk_mul_f32 v[98:99], v[78:79], v[92:93]
	v_mov_b64_e32 v[94:95], v[190:191]
	v_pk_mul_f32 v[96:97], v[78:79], v[94:95] op_sel:[1,0] op_sel_hi:[0,0]
	v_mov_b32_e32 v94, v93
	v_mul_f32_e32 v0, v81, v95
	v_pk_fma_f32 v[78:79], v[78:79], v[92:93], v[96:97] op_sel_hi:[1,0,1]
	v_pk_fma_f32 v[100:101], v[80:81], v[94:95], v[0:1] op_sel_hi:[1,1,0] neg_lo:[0,0,1] neg_hi:[0,0,1]
	v_mov_b32_e32 v92, v95
	v_mul_f32_e32 v0, v81, v93
	v_pk_fma_f32 v[92:93], v[80:81], v[92:93], v[0:1] op_sel_hi:[1,1,0]
	v_sub_f32_e32 v78, v98, v96
	v_mov_b32_e32 v80, v100
	v_mov_b32_e32 v81, v92
.LBB0_304:
	v_mov_b64_e32 v[92:93], v[178:179]
	v_mov_b64_e32 v[94:95], v[180:181]
	v_mov_b32_e32 v87, v86
	v_mov_b32_e32 v96, v86
	v_mov_b32_e32 v97, v86
	v_pk_mul_f32 v[76:77], v[76:77], v[96:97]
	v_pk_mul_f32 v[74:75], v[74:75], v[86:87]
	s_and_b64 vcc, exec, s[40:41]
	v_pk_mul_f32 v[86:87], v[76:77], v[94:95]
	v_pk_mul_f32 v[76:77], v[74:75], v[92:93]
	s_cbranch_vccnz .LBB0_306
	v_lshlrev_b32_e32 v0, 1, v141
	v_lshl_add_u64 v[74:75], v[84:85], 0, v[0:1]
	v_lshl_add_u64 v[92:93], v[82:83], 0, v[0:1]
	v_mov_b64_e32 v[74:75], v[188:189]
	v_pk_mul_f32 v[96:97], v[76:77], v[74:75]
	v_mov_b64_e32 v[92:93], v[192:193]
	v_pk_mul_f32 v[94:95], v[76:77], v[92:93] op_sel:[1,0] op_sel_hi:[0,0]
	v_mov_b32_e32 v92, v75
	v_mul_f32_e32 v0, v87, v93
	v_pk_fma_f32 v[76:77], v[76:77], v[74:75], v[94:95] op_sel_hi:[1,0,1]
	v_pk_fma_f32 v[98:99], v[86:87], v[92:93], v[0:1] op_sel_hi:[1,1,0] neg_lo:[0,0,1] neg_hi:[0,0,1]
	v_mov_b32_e32 v74, v93
	v_mul_f32_e32 v0, v87, v75
	v_pk_fma_f32 v[74:75], v[86:87], v[74:75], v[0:1] op_sel_hi:[1,1,0]
	v_sub_f32_e32 v76, v96, v94
	v_mov_b32_e32 v86, v98
	v_mov_b32_e32 v87, v74

; template <int EPI>
; DI void gemm_epilogue(const Params& p, int layer, f32x4 (&acc)[2][2][4][2], int brow, int bcol, int pn, int wr, int wc,
;                       int fr, int fq, char* smem, int ksplit = -1) {
;     ...
;             for (int n = 0; n < 2; ++n) {
;               const int cih = (wc & 1) * 32 + fq * 8 + n * 4;
;               f32x4 v = acc[ai][bj][m][n];
;               if (normed) {
;                 f32x4 g = *(const f32x4*)(gq + cih);
;                 v = v * rs * g;
;                 if (latent) {
;                   const float2 cs = *(const float2*)(p.ropec + spos * 32 + (cih >> 1));
;                   const float2 sn = *(const float2*)(p.ropes + spos * 32 + (cih >> 1));
;                   f32x4 r;
;                   r[0] = v[0] * cs.x - v[1] * sn.x;
;                   r[1] = v[0] * sn.x + v[1] * cs.x;
;                   r[2] = v[2] * cs.y - v[3] * sn.y;
;                   r[3] = v[2] * sn.y + v[3] * cs.y;
;                   v = r;
;                 }
;                 if (pn == 9) v = v * 0.125f;
.LBB0_310:
	v_mov_b64_e32 v[78:79], v[168:169]
	v_mov_b64_e32 v[80:81], v[170:171]
	v_mov_b32_e32 v86, v76
	v_mov_b32_e32 v87, v76
	v_pk_mul_f32 v[72:73], v[72:73], v[86:87]
	v_pk_mul_f32 v[70:71], v[70:71], v[76:77]
	s_and_b64 vcc, exec, s[40:41]
	v_pk_mul_f32 v[72:73], v[72:73], v[80:81]
	v_pk_mul_f32 v[70:71], v[70:71], v[78:79]
	s_cbranch_vccnz .LBB0_312
	v_lshlrev_b32_e32 v0, 1, v140
	v_lshl_add_u64 v[78:79], v[84:85], 0, v[0:1]
	v_lshl_add_u64 v[80:81], v[82:83], 0, v[0:1]
	v_mov_b64_e32 v[78:79], v[186:187]
	v_pk_mul_f32 v[88:89], v[70:71], v[78:79]
	v_mov_b64_e32 v[80:81], v[190:191]
	v_pk_mul_f32 v[86:87], v[70:71], v[80:81] op_sel:[1,0] op_sel_hi:[0,0]
	v_mov_b32_e32 v80, v79
	v_mul_f32_e32 v0, v73, v81
	v_pk_fma_f32 v[70:71], v[70:71], v[78:79], v[86:87] op_sel_hi:[1,0,1]
	v_pk_fma_f32 v[90:91], v[72:73], v[80:81], v[0:1] op_sel_hi:[1,1,0] neg_lo:[0,0,1] neg_hi:[0,0,1]
	v_mov_b32_e32 v78, v81
	v_mul_f32_e32 v0, v73, v79
	v_pk_fma_f32 v[78:79], v[72:73], v[78:79], v[0:1] op_sel_hi:[1,1,0]
	v_sub_f32_e32 v70, v88, v86
	v_mov_b32_e32 v72, v90
	v_mov_b32_e32 v73, v78

; template <int EPI>
; DI void gemm_epilogue(const Params& p, int layer, f32x4 (&acc)[2][2][4][2], int brow, int bcol, int pn, int wr, int wc,
;                       int fr, int fq, char* smem, int ksplit = -1) {
;     ...
;             for (int n = 0; n < 2; ++n) {
;               const int cih = (wc & 1) * 32 + fq * 8 + n * 4;
;               f32x4 v = acc[ai][bj][m][n];
;               if (normed) {
;                 f32x4 g = *(const f32x4*)(gq + cih);
;                 v = v * rs * g;
;                 if (latent) {
;                   const float2 cs = *(const float2*)(p.ropec + spos * 32 + (cih >> 1));
;                   const float2 sn = *(const float2*)(p.ropes + spos * 32 + (cih >> 1));
;                   f32x4 r;
;                   r[0] = v[0] * cs.x - v[1] * sn.x;
;                   r[1] = v[0] * sn.x + v[1] * cs.x;
;                   r[2] = v[2] * cs.y - v[3] * sn.y;
;                   r[3] = v[2] * sn.y + v[3] * cs.y;
;                   v = r;
;                 }
;                 if (pn == 9) v = v * 0.125f;
.LBB0_313:
	v_mov_b64_e32 v[78:79], v[178:179]
	v_mov_b64_e32 v[80:81], v[180:181]
	v_mov_b32_e32 v86, v76
	v_mov_b32_e32 v87, v76
	v_pk_mul_f32 v[66:67], v[66:67], v[76:77]
	v_pk_mul_f32 v[68:69], v[68:69], v[86:87]
	s_and_b64 vcc, exec, s[40:41]
	v_pk_mul_f32 v[68:69], v[68:69], v[80:81]
	v_pk_mul_f32 v[66:67], v[66:67], v[78:79]
	s_cbranch_vccnz .LBB0_315
	v_lshlrev_b32_e32 v0, 1, v141
	v_lshl_add_u64 v[76:77], v[84:85], 0, v[0:1]
	v_lshl_add_u64 v[78:79], v[82:83], 0, v[0:1]
	v_mov_b64_e32 v[76:77], v[188:189]
	v_pk_mul_f32 v[82:83], v[66:67], v[76:77]
	v_mov_b64_e32 v[78:79], v[192:193]
	v_pk_mul_f32 v[80:81], v[66:67], v[78:79] op_sel:[1,0] op_sel_hi:[0,0]
	v_mov_b32_e32 v78, v77
	v_mul_f32_e32 v0, v69, v79
	v_pk_fma_f32 v[66:67], v[66:67], v[76:77], v[80:81] op_sel_hi:[1,0,1]
	v_pk_fma_f32 v[84:85], v[68:69], v[78:79], v[0:1] op_sel_hi:[1,1,0] neg_lo:[0,0,1] neg_hi:[0,0,1]
	v_mov_b32_e32 v76, v79
	v_mul_f32_e32 v0, v69, v77
	v_pk_fma_f32 v[76:77], v[68:69], v[76:77], v[0:1] op_sel_hi:[1,1,0]
	v_sub_f32_e32 v66, v82, v80
	v_mov_b32_e32 v68, v84
	v_mov_b32_e32 v69, v76

; template <int EPI>
; DI void gemm_epilogue(const Params& p, int layer, f32x4 (&acc)[2][2][4][2], int brow, int bcol, int pn, int wr, int wc,
;                       int fr, int fq, char* smem, int ksplit = -1) {
;     ...
;           const int rl = ai * 128 + wr * 64 + m * 16 + fr;
;           const int row = brow + rl;
;           const int spos = row & (SEQ - 1);
; #pragma unroll
;           for (int bj = 0; bj < 2; ++bj) {
;             const bool normed = (pn == 9) || (bj == 0);
;             float rs = 1.f;
;             if (normed) {
;               float tot = xch[rl * 8 + bj * 4 + wc] + xch[rl * 8 + bj * 4 + (wc ^ 1)];
;               rs = __builtin_amdgcn_rsqf(tot * (1.f / 64.f) + EPSN);
;             }
;             u32x4 o;
; #pragma unroll
;             for (int n = 0; n < 2; ++n) {
;               const int cih = (wc & 1) * 32 + fq * 8 + n * 4;
;               f32x4 v = acc[ai][bj][m][n];
;               if (normed) {
;                 f32x4 g = *(const f32x4*)(gq + cih);
;                 v = v * rs * g;
;                 if (latent) {
;                   const float2 cs = *(const float2*)(p.ropec + spos * 32 + (cih >> 1));
;                   const float2 sn = *(const float2*)(p.ropes + spos * 32 + (cih >> 1));
;                   f32x4 r;
;                   r[0] = v[0] * cs.x - v[1] * sn.x;
;                   r[1] = v[0] * sn.x + v[1] * cs.x;
;                   r[2] = v[2] * cs.y - v[3] * sn.y;
;                   r[3] = v[2] * sn.y + v[3] * cs.y;
;                   v = r;
;                 }
;                 if (pn == 9) v = v * 0.125f;
.LBB0_316:
	v_cvt_pk_bf16_f32 v70, v70, v71
	v_cvt_pk_bf16_f32 v71, v72, v73
	v_cvt_pk_bf16_f32 v72, v66, v67
	v_cvt_pk_bf16_f32 v73, v68, v69
	global_store_dwordx4 v[74:75], v[70:73], off offset:256
	v_add_u32_e32 v0, 0x80, v154
	v_mov_b64_e32 v[76:77], v[168:169]
	v_mov_b64_e32 v[78:79], v[170:171]
	v_lshlrev_b32_e32 v66, 3, v0
	v_or_b32_e32 v73, s13, v66
	v_bitop3_b32 v66, v66, 1, s13 bitop3:0x36
	v_lshl_add_u32 v72, v73, 2, s24
	v_lshl_add_u32 v66, v66, 2, s24
	ds_read_b32 v67, v72
	ds_read_b32 v66, v66
	v_add_u32_e32 v74, s22, v0
	v_lshlrev_b32_e32 v0, 7, v74
	v_readlane_b32 s60, v254, 45
	v_and_b32_e32 v0, 0x3e780, v0
	s_waitcnt lgkmcnt(0)
	v_add_f32_e32 v66, v67, v66
	v_fmamk_f32 v66, v66, 0x3c800000, v236
	v_rsq_f32_e32 v70, v66
	v_readlane_b32 s66, v254, 51
	v_readlane_b32 s67, v254, 52
	v_readlane_b32 s68, v254, 53
	v_readlane_b32 s69, v254, 54
	v_pk_mul_f32 v[62:63], v[62:63], v[70:71] op_sel_hi:[1,0]
	v_pk_mul_f32 v[64:65], v[64:65], v[70:71] op_sel_hi:[1,0]
	s_and_b64 vcc, exec, s[40:41]
	v_lshl_add_u64 v[68:69], s[66:67], 0, v[0:1]
	v_lshl_add_u64 v[66:67], s[68:69], 0, v[0:1]
	v_lshl_add_u64 v[184:185], v[68:69], 0, v[182:183]
	global_load_dwordx4 v[186:189], v[184:185], off
	v_lshl_add_u64 v[184:185], v[66:67], 0, v[182:183]
	global_load_dwordx4 v[190:193], v[184:185], off
	v_readlane_b32 s61, v254, 46
	v_readlane_b32 s62, v254, 47
	v_readlane_b32 s63, v254, 48
	v_readlane_b32 s64, v254, 49
	v_readlane_b32 s65, v254, 50
	v_readlane_b32 s70, v254, 55
	v_readlane_b32 s71, v254, 56
	v_readlane_b32 s72, v254, 57
	v_readlane_b32 s73, v254, 58
	v_readlane_b32 s74, v254, 59
	v_readlane_b32 s75, v254, 60
	v_pk_mul_f32 v[64:65], v[78:79], v[64:65]
	v_pk_mul_f32 v[62:63], v[76:77], v[62:63]
	s_cbranch_vccnz .LBB0_318
	v_lshlrev_b32_e32 v0, 1, v140
	v_lshl_add_u64 v[76:77], v[68:69], 0, v[0:1]
	v_lshl_add_u64 v[78:79], v[66:67], 0, v[0:1]
	s_waitcnt vmcnt(0)
	v_mov_b64_e32 v[76:77], v[186:187]
	v_pk_mul_f32 v[82:83], v[62:63], v[76:77]
	v_mov_b64_e32 v[78:79], v[190:191]
	v_pk_mul_f32 v[80:81], v[62:63], v[78:79] op_sel:[1,0] op_sel_hi:[0,0]
	v_mov_b32_e32 v78, v77
	v_mul_f32_e32 v0, v65, v79
	v_pk_fma_f32 v[62:63], v[62:63], v[76:77], v[80:81] op_sel_hi:[1,0,1]
	v_pk_fma_f32 v[84:85], v[64:65], v[78:79], v[0:1] op_sel_hi:[1,1,0] neg_lo:[0,0,1] neg_hi:[0,0,1]
	v_mov_b32_e32 v76, v79
	v_mul_f32_e32 v0, v65, v77
	v_pk_fma_f32 v[76:77], v[64:65], v[76:77], v[0:1] op_sel_hi:[1,1,0]
	v_sub_f32_e32 v62, v82, v80
	v_mov_b32_e32 v64, v84
	v_mov_b32_e32 v65, v76
.LBB0_318:
	v_mov_b64_e32 v[76:77], v[178:179]
	v_mov_b64_e32 v[78:79], v[180:181]
	v_mov_b32_e32 v71, v70
	v_mov_b32_e32 v80, v70
	v_mov_b32_e32 v81, v70
	v_pk_mul_f32 v[60:61], v[60:61], v[80:81]
	v_pk_mul_f32 v[58:59], v[58:59], v[70:71]
	s_and_b64 vcc, exec, s[40:41]
	v_pk_mul_f32 v[70:71], v[60:61], v[78:79]
	v_pk_mul_f32 v[60:61], v[58:59], v[76:77]
	s_cbranch_vccnz .LBB0_320
	v_lshlrev_b32_e32 v0, 1, v141
	v_lshl_add_u64 v[58:59], v[68:69], 0, v[0:1]
	v_lshl_add_u64 v[76:77], v[66:67], 0, v[0:1]
	v_mov_b64_e32 v[58:59], v[188:189]
	v_pk_mul_f32 v[80:81], v[60:61], v[58:59]
	v_mov_b64_e32 v[76:77], v[192:193]
	v_pk_mul_f32 v[78:79], v[60:61], v[76:77] op_sel:[1,0] op_sel_hi:[0,0]
	v_mov_b32_e32 v76, v59
	v_mul_f32_e32 v0, v71, v77
	v_pk_fma_f32 v[60:61], v[60:61], v[58:59], v[78:79] op_sel_hi:[1,0,1]
	v_pk_fma_f32 v[82:83], v[70:71], v[76:77], v[0:1] op_sel_hi:[1,1,0] neg_lo:[0,0,1] neg_hi:[0,0,1]
	v_mov_b32_e32 v58, v77
	v_mul_f32_e32 v0, v71, v59
	v_pk_fma_f32 v[58:59], v[70:71], v[58:59], v[0:1] op_sel_hi:[1,1,0]
	v_sub_f32_e32 v60, v80, v78
	v_mov_b32_e32 v70, v82
	v_mov_b32_e32 v71, v58

; template <int EPI>
; DI void gemm_epilogue(const Params& p, int layer, f32x4 (&acc)[2][2][4][2], int brow, int bcol, int pn, int wr, int wc,
;                       int fr, int fq, char* smem, int ksplit = -1) {
;     ...
;             for (int n = 0; n < 2; ++n) {
;               const int cih = (wc & 1) * 32 + fq * 8 + n * 4;
;               f32x4 v = acc[ai][bj][m][n];
;               if (normed) {
;                 f32x4 g = *(const f32x4*)(gq + cih);
;                 v = v * rs * g;
;                 if (latent) {
;                   const float2 cs = *(const float2*)(p.ropec + spos * 32 + (cih >> 1));
;                   const float2 sn = *(const float2*)(p.ropes + spos * 32 + (cih >> 1));
;                   f32x4 r;
;                   r[0] = v[0] * cs.x - v[1] * sn.x;
;                   r[1] = v[0] * sn.x + v[1] * cs.x;
;                   r[2] = v[2] * cs.y - v[3] * sn.y;
;                   r[3] = v[2] * sn.y + v[3] * cs.y;
;                   v = r;
;                 }
;                 if (pn == 9) v = v * 0.125f;
.LBB0_324:
	v_mov_b64_e32 v[62:63], v[168:169]
	v_mov_b64_e32 v[64:65], v[170:171]
	v_mov_b32_e32 v70, v60
	v_mov_b32_e32 v71, v60
	v_pk_mul_f32 v[56:57], v[56:57], v[70:71]
	v_pk_mul_f32 v[54:55], v[54:55], v[60:61]
	s_and_b64 vcc, exec, s[40:41]
	v_pk_mul_f32 v[56:57], v[56:57], v[64:65]
	v_pk_mul_f32 v[54:55], v[54:55], v[62:63]
	s_cbranch_vccnz .LBB0_326
	v_lshlrev_b32_e32 v0, 1, v140
	v_lshl_add_u64 v[62:63], v[68:69], 0, v[0:1]
	v_lshl_add_u64 v[64:65], v[66:67], 0, v[0:1]
	v_mov_b64_e32 v[62:63], v[186:187]
	v_pk_mul_f32 v[72:73], v[54:55], v[62:63]
	v_mov_b64_e32 v[64:65], v[190:191]
	v_pk_mul_f32 v[70:71], v[54:55], v[64:65] op_sel:[1,0] op_sel_hi:[0,0]
	v_mov_b32_e32 v64, v63
	v_mul_f32_e32 v0, v57, v65
	v_pk_fma_f32 v[54:55], v[54:55], v[62:63], v[70:71] op_sel_hi:[1,0,1]
	v_pk_fma_f32 v[74:75], v[56:57], v[64:65], v[0:1] op_sel_hi:[1,1,0] neg_lo:[0,0,1] neg_hi:[0,0,1]
	v_mov_b32_e32 v62, v65
	v_mul_f32_e32 v0, v57, v63
	v_pk_fma_f32 v[62:63], v[56:57], v[62:63], v[0:1] op_sel_hi:[1,1,0]
	v_sub_f32_e32 v54, v72, v70
	v_mov_b32_e32 v56, v74
	v_mov_b32_e32 v57, v62

; template <int EPI>
; DI void gemm_epilogue(const Params& p, int layer, f32x4 (&acc)[2][2][4][2], int brow, int bcol, int pn, int wr, int wc,
;                       int fr, int fq, char* smem, int ksplit = -1) {
;     ...
;             for (int n = 0; n < 2; ++n) {
;               const int cih = (wc & 1) * 32 + fq * 8 + n * 4;
;               f32x4 v = acc[ai][bj][m][n];
;               if (normed) {
;                 f32x4 g = *(const f32x4*)(gq + cih);
;                 v = v * rs * g;
;                 if (latent) {
;                   const float2 cs = *(const float2*)(p.ropec + spos * 32 + (cih >> 1));
;                   const float2 sn = *(const float2*)(p.ropes + spos * 32 + (cih >> 1));
;                   f32x4 r;
;                   r[0] = v[0] * cs.x - v[1] * sn.x;
;                   r[1] = v[0] * sn.x + v[1] * cs.x;
;                   r[2] = v[2] * cs.y - v[3] * sn.y;
;                   r[3] = v[2] * sn.y + v[3] * cs.y;
;                   v = r;
;                 }
;                 if (pn == 9) v = v * 0.125f;
.LBB0_327:
	v_mov_b64_e32 v[62:63], v[178:179]
	v_mov_b64_e32 v[64:65], v[180:181]
	v_mov_b32_e32 v70, v60
	v_mov_b32_e32 v71, v60
	v_pk_mul_f32 v[50:51], v[50:51], v[60:61]
	v_pk_mul_f32 v[52:53], v[52:53], v[70:71]
	s_and_b64 vcc, exec, s[40:41]
	v_pk_mul_f32 v[52:53], v[52:53], v[64:65]
	v_pk_mul_f32 v[50:51], v[50:51], v[62:63]
	s_cbranch_vccnz .LBB0_329
	v_lshlrev_b32_e32 v0, 1, v141
	v_lshl_add_u64 v[60:61], v[68:69], 0, v[0:1]
	v_lshl_add_u64 v[62:63], v[66:67], 0, v[0:1]
	v_mov_b64_e32 v[60:61], v[188:189]
	v_pk_mul_f32 v[66:67], v[50:51], v[60:61]
	v_mov_b64_e32 v[62:63], v[192:193]
	v_pk_mul_f32 v[64:65], v[50:51], v[62:63] op_sel:[1,0] op_sel_hi:[0,0]
	v_mov_b32_e32 v62, v61
	v_mul_f32_e32 v0, v53, v63
	v_pk_fma_f32 v[50:51], v[50:51], v[60:61], v[64:65] op_sel_hi:[1,0,1]
	v_pk_fma_f32 v[68:69], v[52:53], v[62:63], v[0:1] op_sel_hi:[1,1,0] neg_lo:[0,0,1] neg_hi:[0,0,1]
	v_mov_b32_e32 v60, v63
	v_mul_f32_e32 v0, v53, v61
	v_pk_fma_f32 v[60:61], v[52:53], v[60:61], v[0:1] op_sel_hi:[1,1,0]
	v_sub_f32_e32 v50, v66, v64
	v_mov_b32_e32 v52, v68
	v_mov_b32_e32 v53, v60

; template <int EPI>
; DI void gemm_epilogue(const Params& p, int layer, f32x4 (&acc)[2][2][4][2], int brow, int bcol, int pn, int wr, int wc,
;                       int fr, int fq, char* smem, int ksplit = -1) {
;     ...
;           const int rl = ai * 128 + wr * 64 + m * 16 + fr;
;           const int row = brow + rl;
;           const int spos = row & (SEQ - 1);
; #pragma unroll
;           for (int bj = 0; bj < 2; ++bj) {
;             const bool normed = (pn == 9) || (bj == 0);
;             float rs = 1.f;
;             if (normed) {
;               float tot = xch[rl * 8 + bj * 4 + wc] + xch[rl * 8 + bj * 4 + (wc ^ 1)];
;               rs = __builtin_amdgcn_rsqf(tot * (1.f / 64.f) + EPSN);
;             }
;             u32x4 o;
; #pragma unroll
;             for (int n = 0; n < 2; ++n) {
;               const int cih = (wc & 1) * 32 + fq * 8 + n * 4;
;               f32x4 v = acc[ai][bj][m][n];
;               if (normed) {
;                 f32x4 g = *(const f32x4*)(gq + cih);
;                 v = v * rs * g;
;                 if (latent) {
;                   const float2 cs = *(const float2*)(p.ropec + spos * 32 + (cih >> 1));
;                   const float2 sn = *(const float2*)(p.ropes + spos * 32 + (cih >> 1));
;                   f32x4 r;
;                   r[0] = v[0] * cs.x - v[1] * sn.x;
;                   r[1] = v[0] * sn.x + v[1] * cs.x;
;                   r[2] = v[2] * cs.y - v[3] * sn.y;
;                   r[3] = v[2] * sn.y + v[3] * cs.y;
;                   v = r;
;                 }
;                 if (pn == 9) v = v * 0.125f;
.LBB0_330:
	v_cvt_pk_bf16_f32 v54, v54, v55
	v_cvt_pk_bf16_f32 v55, v56, v57
	v_cvt_pk_bf16_f32 v56, v50, v51
	v_cvt_pk_bf16_f32 v57, v52, v53
	global_store_dwordx4 v[58:59], v[54:57], off offset:256
	v_mov_b64_e32 v[60:61], v[168:169]
	v_mov_b64_e32 v[62:63], v[170:171]
	v_add_u32_e32 v0, 0x90, v154
	v_lshlrev_b32_e32 v50, 3, v0
	v_or_b32_e32 v57, s13, v50
	v_bitop3_b32 v50, v50, 1, s13 bitop3:0x36
	v_lshl_add_u32 v56, v57, 2, s24
	v_lshl_add_u32 v50, v50, 2, s24
	ds_read_b32 v51, v56
	ds_read_b32 v50, v50
	v_add_u32_e32 v58, s22, v0
	v_lshlrev_b32_e32 v0, 7, v58
	v_readlane_b32 s60, v254, 45
	v_and_b32_e32 v0, 0x3ef80, v0
	s_waitcnt lgkmcnt(0)
	v_add_f32_e32 v50, v51, v50
	v_fmamk_f32 v50, v50, 0x3c800000, v236
	v_rsq_f32_e32 v54, v50
	v_readlane_b32 s66, v254, 51
	v_readlane_b32 s67, v254, 52
	v_readlane_b32 s68, v254, 53
	v_readlane_b32 s69, v254, 54
	v_pk_mul_f32 v[46:47], v[46:47], v[54:55] op_sel_hi:[1,0]
	v_pk_mul_f32 v[48:49], v[48:49], v[54:55] op_sel_hi:[1,0]
	s_and_b64 vcc, exec, s[40:41]
	v_lshl_add_u64 v[52:53], s[66:67], 0, v[0:1]
	v_lshl_add_u64 v[50:51], s[68:69], 0, v[0:1]
	v_lshl_add_u64 v[184:185], v[52:53], 0, v[182:183]
	global_load_dwordx4 v[186:189], v[184:185], off
	v_lshl_add_u64 v[184:185], v[50:51], 0, v[182:183]
	global_load_dwordx4 v[190:193], v[184:185], off
	v_readlane_b32 s61, v254, 46
	v_readlane_b32 s62, v254, 47
	v_readlane_b32 s63, v254, 48
	v_readlane_b32 s64, v254, 49
	v_readlane_b32 s65, v254, 50
	v_readlane_b32 s70, v254, 55
	v_readlane_b32 s71, v254, 56
	v_readlane_b32 s72, v254, 57
	v_readlane_b32 s73, v254, 58
	v_readlane_b32 s74, v254, 59
	v_readlane_b32 s75, v254, 60
	v_pk_mul_f32 v[48:49], v[62:63], v[48:49]
	v_pk_mul_f32 v[46:47], v[60:61], v[46:47]
	s_cbranch_vccnz .LBB0_332
	v_lshlrev_b32_e32 v0, 1, v140
	v_lshl_add_u64 v[60:61], v[52:53], 0, v[0:1]
	v_lshl_add_u64 v[62:63], v[50:51], 0, v[0:1]
	s_waitcnt vmcnt(0)
	v_mov_b64_e32 v[60:61], v[186:187]
	v_pk_mul_f32 v[66:67], v[46:47], v[60:61]
	v_mov_b64_e32 v[62:63], v[190:191]
	v_pk_mul_f32 v[64:65], v[46:47], v[62:63] op_sel:[1,0] op_sel_hi:[0,0]
	v_mov_b32_e32 v62, v61
	v_mul_f32_e32 v0, v49, v63
	v_pk_fma_f32 v[46:47], v[46:47], v[60:61], v[64:65] op_sel_hi:[1,0,1]
	v_pk_fma_f32 v[68:69], v[48:49], v[62:63], v[0:1] op_sel_hi:[1,1,0] neg_lo:[0,0,1] neg_hi:[0,0,1]
	v_mov_b32_e32 v60, v63
	v_mul_f32_e32 v0, v49, v61
	v_pk_fma_f32 v[60:61], v[48:49], v[60:61], v[0:1] op_sel_hi:[1,1,0]
	v_sub_f32_e32 v46, v66, v64
	v_mov_b32_e32 v48, v68
	v_mov_b32_e32 v49, v60
.LBB0_332:
	v_mov_b64_e32 v[60:61], v[178:179]
	v_mov_b64_e32 v[62:63], v[180:181]
	v_mov_b32_e32 v55, v54
	v_mov_b32_e32 v64, v54
	v_mov_b32_e32 v65, v54
	v_pk_mul_f32 v[44:45], v[44:45], v[64:65]
	v_pk_mul_f32 v[42:43], v[42:43], v[54:55]
	s_and_b64 vcc, exec, s[40:41]
	v_pk_mul_f32 v[54:55], v[44:45], v[62:63]
	v_pk_mul_f32 v[44:45], v[42:43], v[60:61]
	s_cbranch_vccnz .LBB0_334
	v_lshlrev_b32_e32 v0, 1, v141
	v_lshl_add_u64 v[42:43], v[52:53], 0, v[0:1]
	v_lshl_add_u64 v[60:61], v[50:51], 0, v[0:1]
	v_mov_b64_e32 v[42:43], v[188:189]
	v_pk_mul_f32 v[64:65], v[44:45], v[42:43]
	v_mov_b64_e32 v[60:61], v[192:193]
	v_pk_mul_f32 v[62:63], v[44:45], v[60:61] op_sel:[1,0] op_sel_hi:[0,0]
	v_mov_b32_e32 v60, v43
	v_mul_f32_e32 v0, v55, v61
	v_pk_fma_f32 v[44:45], v[44:45], v[42:43], v[62:63] op_sel_hi:[1,0,1]
	v_pk_fma_f32 v[66:67], v[54:55], v[60:61], v[0:1] op_sel_hi:[1,1,0] neg_lo:[0,0,1] neg_hi:[0,0,1]
	v_mov_b32_e32 v42, v61
	v_mul_f32_e32 v0, v55, v43
	v_pk_fma_f32 v[42:43], v[54:55], v[42:43], v[0:1] op_sel_hi:[1,1,0]
	v_sub_f32_e32 v44, v64, v62
	v_mov_b32_e32 v54, v66
	v_mov_b32_e32 v55, v42

; template <int EPI>
; DI void gemm_epilogue(const Params& p, int layer, f32x4 (&acc)[2][2][4][2], int brow, int bcol, int pn, int wr, int wc,
;                       int fr, int fq, char* smem, int ksplit = -1) {
;     ...
;             for (int n = 0; n < 2; ++n) {
;               const int cih = (wc & 1) * 32 + fq * 8 + n * 4;
;               f32x4 v = acc[ai][bj][m][n];
;               if (normed) {
;                 f32x4 g = *(const f32x4*)(gq + cih);
;                 v = v * rs * g;
;                 if (latent) {
;                   const float2 cs = *(const float2*)(p.ropec + spos * 32 + (cih >> 1));
;                   const float2 sn = *(const float2*)(p.ropes + spos * 32 + (cih >> 1));
;                   f32x4 r;
;                   r[0] = v[0] * cs.x - v[1] * sn.x;
;                   r[1] = v[0] * sn.x + v[1] * cs.x;
;                   r[2] = v[2] * cs.y - v[3] * sn.y;
;                   r[3] = v[2] * sn.y + v[3] * cs.y;
;                   v = r;
;                 }
;                 if (pn == 9) v = v * 0.125f;
.LBB0_338:
	v_mov_b64_e32 v[46:47], v[168:169]
	v_mov_b64_e32 v[48:49], v[170:171]
	v_mov_b32_e32 v54, v44
	v_mov_b32_e32 v55, v44
	v_pk_mul_f32 v[40:41], v[40:41], v[54:55]
	v_pk_mul_f32 v[38:39], v[38:39], v[44:45]
	s_and_b64 vcc, exec, s[40:41]
	v_pk_mul_f32 v[40:41], v[40:41], v[48:49]
	v_pk_mul_f32 v[38:39], v[38:39], v[46:47]
	s_cbranch_vccnz .LBB0_340
	v_lshlrev_b32_e32 v0, 1, v140
	v_lshl_add_u64 v[46:47], v[52:53], 0, v[0:1]
	v_lshl_add_u64 v[48:49], v[50:51], 0, v[0:1]
	v_mov_b64_e32 v[46:47], v[186:187]
	v_pk_mul_f32 v[56:57], v[38:39], v[46:47]
	v_mov_b64_e32 v[48:49], v[190:191]
	v_pk_mul_f32 v[54:55], v[38:39], v[48:49] op_sel:[1,0] op_sel_hi:[0,0]
	v_mov_b32_e32 v48, v47
	v_mul_f32_e32 v0, v41, v49
	v_pk_fma_f32 v[38:39], v[38:39], v[46:47], v[54:55] op_sel_hi:[1,0,1]
	v_pk_fma_f32 v[58:59], v[40:41], v[48:49], v[0:1] op_sel_hi:[1,1,0] neg_lo:[0,0,1] neg_hi:[0,0,1]
	v_mov_b32_e32 v46, v49
	v_mul_f32_e32 v0, v41, v47
	v_pk_fma_f32 v[46:47], v[40:41], v[46:47], v[0:1] op_sel_hi:[1,1,0]
	v_sub_f32_e32 v38, v56, v54
	v_mov_b32_e32 v40, v58
	v_mov_b32_e32 v41, v46

; template <int EPI>
; DI void gemm_epilogue(const Params& p, int layer, f32x4 (&acc)[2][2][4][2], int brow, int bcol, int pn, int wr, int wc,
;                       int fr, int fq, char* smem, int ksplit = -1) {
;     ...
;             for (int n = 0; n < 2; ++n) {
;               const int cih = (wc & 1) * 32 + fq * 8 + n * 4;
;               f32x4 v = acc[ai][bj][m][n];
;               if (normed) {
;                 f32x4 g = *(const f32x4*)(gq + cih);
;                 v = v * rs * g;
;                 if (latent) {
;                   const float2 cs = *(const float2*)(p.ropec + spos * 32 + (cih >> 1));
;                   const float2 sn = *(const float2*)(p.ropes + spos * 32 + (cih >> 1));
;                   f32x4 r;
;                   r[0] = v[0] * cs.x - v[1] * sn.x;
;                   r[1] = v[0] * sn.x + v[1] * cs.x;
;                   r[2] = v[2] * cs.y - v[3] * sn.y;
;                   r[3] = v[2] * sn.y + v[3] * cs.y;
;                   v = r;
;                 }
;                 if (pn == 9) v = v * 0.125f;
.LBB0_341:
	v_mov_b64_e32 v[46:47], v[178:179]
	v_mov_b64_e32 v[48:49], v[180:181]
	v_mov_b32_e32 v54, v44
	v_mov_b32_e32 v55, v44
	v_pk_mul_f32 v[34:35], v[34:35], v[44:45]
	v_pk_mul_f32 v[36:37], v[36:37], v[54:55]
	s_and_b64 vcc, exec, s[40:41]
	v_pk_mul_f32 v[36:37], v[36:37], v[48:49]
	v_pk_mul_f32 v[34:35], v[34:35], v[46:47]
	s_cbranch_vccnz .LBB0_343
	v_lshlrev_b32_e32 v0, 1, v141
	v_lshl_add_u64 v[44:45], v[52:53], 0, v[0:1]
	v_lshl_add_u64 v[46:47], v[50:51], 0, v[0:1]
	v_mov_b64_e32 v[44:45], v[188:189]
	v_pk_mul_f32 v[50:51], v[34:35], v[44:45]
	v_mov_b64_e32 v[46:47], v[192:193]
	v_pk_mul_f32 v[48:49], v[34:35], v[46:47] op_sel:[1,0] op_sel_hi:[0,0]
	v_mov_b32_e32 v46, v45
	v_mul_f32_e32 v0, v37, v47
	v_pk_fma_f32 v[34:35], v[34:35], v[44:45], v[48:49] op_sel_hi:[1,0,1]
	v_pk_fma_f32 v[52:53], v[36:37], v[46:47], v[0:1] op_sel_hi:[1,1,0] neg_lo:[0,0,1] neg_hi:[0,0,1]
	v_mov_b32_e32 v44, v47
	v_mul_f32_e32 v0, v37, v45
	v_pk_fma_f32 v[44:45], v[36:37], v[44:45], v[0:1] op_sel_hi:[1,1,0]
	v_sub_f32_e32 v34, v50, v48
	v_mov_b32_e32 v36, v52
	v_mov_b32_e32 v37, v44

; template <int EPI>
; DI void gemm_epilogue(const Params& p, int layer, f32x4 (&acc)[2][2][4][2], int brow, int bcol, int pn, int wr, int wc,
;                       int fr, int fq, char* smem, int ksplit = -1) {
;     ...
;           const int rl = ai * 128 + wr * 64 + m * 16 + fr;
;           const int row = brow + rl;
;           const int spos = row & (SEQ - 1);
; #pragma unroll
;           for (int bj = 0; bj < 2; ++bj) {
;             const bool normed = (pn == 9) || (bj == 0);
;             float rs = 1.f;
;             if (normed) {
;               float tot = xch[rl * 8 + bj * 4 + wc] + xch[rl * 8 + bj * 4 + (wc ^ 1)];
;               rs = __builtin_amdgcn_rsqf(tot * (1.f / 64.f) + EPSN);
;             }
;             u32x4 o;
; #pragma unroll
;             for (int n = 0; n < 2; ++n) {
;               const int cih = (wc & 1) * 32 + fq * 8 + n * 4;
;               f32x4 v = acc[ai][bj][m][n];
;               if (normed) {
;                 f32x4 g = *(const f32x4*)(gq + cih);
;                 v = v * rs * g;
;                 if (latent) {
;                   const float2 cs = *(const float2*)(p.ropec + spos * 32 + (cih >> 1));
;                   const float2 sn = *(const float2*)(p.ropes + spos * 32 + (cih >> 1));
;                   f32x4 r;
;                   r[0] = v[0] * cs.x - v[1] * sn.x;
;                   r[1] = v[0] * sn.x + v[1] * cs.x;
;                   r[2] = v[2] * cs.y - v[3] * sn.y;
;                   r[3] = v[2] * sn.y + v[3] * cs.y;
;                   v = r;
;                 }
;                 if (pn == 9) v = v * 0.125f;
.LBB0_344:
	v_cvt_pk_bf16_f32 v38, v38, v39
	v_cvt_pk_bf16_f32 v39, v40, v41
	v_cvt_pk_bf16_f32 v40, v34, v35
	v_cvt_pk_bf16_f32 v41, v36, v37
	global_store_dwordx4 v[42:43], v[38:41], off offset:256
	v_mov_b64_e32 v[44:45], v[168:169]
	v_mov_b64_e32 v[46:47], v[170:171]
	v_add_u32_e32 v0, 0xa0, v154
	v_lshlrev_b32_e32 v34, 3, v0
	v_or_b32_e32 v41, s13, v34
	v_bitop3_b32 v34, v34, 1, s13 bitop3:0x36
	v_lshl_add_u32 v40, v41, 2, s24
	v_lshl_add_u32 v34, v34, 2, s24
	ds_read_b32 v35, v40
	ds_read_b32 v34, v34
	v_add_u32_e32 v42, s22, v0
	v_lshlrev_b32_e32 v0, 7, v42
	v_readlane_b32 s60, v254, 45
	v_and_b32_e32 v0, 0x3f780, v0
	s_waitcnt lgkmcnt(0)
	v_add_f32_e32 v34, v35, v34
	v_fmamk_f32 v34, v34, 0x3c800000, v236
	v_rsq_f32_e32 v38, v34
	v_readlane_b32 s66, v254, 51
	v_readlane_b32 s67, v254, 52
	v_readlane_b32 s68, v254, 53
	v_readlane_b32 s69, v254, 54
	v_pk_mul_f32 v[30:31], v[30:31], v[38:39] op_sel_hi:[1,0]
	v_pk_mul_f32 v[32:33], v[32:33], v[38:39] op_sel_hi:[1,0]
	s_and_b64 vcc, exec, s[40:41]
	v_lshl_add_u64 v[36:37], s[66:67], 0, v[0:1]
	v_lshl_add_u64 v[34:35], s[68:69], 0, v[0:1]
	v_lshl_add_u64 v[184:185], v[36:37], 0, v[182:183]
	global_load_dwordx4 v[186:189], v[184:185], off
	v_lshl_add_u64 v[184:185], v[34:35], 0, v[182:183]
	global_load_dwordx4 v[190:193], v[184:185], off
	v_readlane_b32 s61, v254, 46
	v_readlane_b32 s62, v254, 47
	v_readlane_b32 s63, v254, 48
	v_readlane_b32 s64, v254, 49
	v_readlane_b32 s65, v254, 50
	v_readlane_b32 s70, v254, 55
	v_readlane_b32 s71, v254, 56
	v_readlane_b32 s72, v254, 57
	v_readlane_b32 s73, v254, 58
	v_readlane_b32 s74, v254, 59
	v_readlane_b32 s75, v254, 60
	v_pk_mul_f32 v[32:33], v[46:47], v[32:33]
	v_pk_mul_f32 v[30:31], v[44:45], v[30:31]
	s_cbranch_vccnz .LBB0_346
	v_lshlrev_b32_e32 v0, 1, v140
	v_lshl_add_u64 v[44:45], v[36:37], 0, v[0:1]
	v_lshl_add_u64 v[46:47], v[34:35], 0, v[0:1]
	s_waitcnt vmcnt(0)
	v_mov_b64_e32 v[44:45], v[186:187]
	v_pk_mul_f32 v[50:51], v[30:31], v[44:45]
	v_mov_b64_e32 v[46:47], v[190:191]
	v_pk_mul_f32 v[48:49], v[30:31], v[46:47] op_sel:[1,0] op_sel_hi:[0,0]
	v_mov_b32_e32 v46, v45
	v_mul_f32_e32 v0, v33, v47
	v_pk_fma_f32 v[30:31], v[30:31], v[44:45], v[48:49] op_sel_hi:[1,0,1]
	v_pk_fma_f32 v[52:53], v[32:33], v[46:47], v[0:1] op_sel_hi:[1,1,0] neg_lo:[0,0,1] neg_hi:[0,0,1]
	v_mov_b32_e32 v44, v47
	v_mul_f32_e32 v0, v33, v45
	v_pk_fma_f32 v[44:45], v[32:33], v[44:45], v[0:1] op_sel_hi:[1,1,0]
	v_sub_f32_e32 v30, v50, v48
	v_mov_b32_e32 v32, v52
	v_mov_b32_e32 v33, v44
.LBB0_346:
	v_mov_b64_e32 v[44:45], v[178:179]
	v_mov_b64_e32 v[46:47], v[180:181]
	v_mov_b32_e32 v39, v38
	v_mov_b32_e32 v48, v38
	v_mov_b32_e32 v49, v38
	v_pk_mul_f32 v[28:29], v[28:29], v[48:49]
	v_pk_mul_f32 v[26:27], v[26:27], v[38:39]
	s_and_b64 vcc, exec, s[40:41]
	v_pk_mul_f32 v[38:39], v[28:29], v[46:47]
	v_pk_mul_f32 v[28:29], v[26:27], v[44:45]
	s_cbranch_vccnz .LBB0_348
	v_lshlrev_b32_e32 v0, 1, v141
	v_lshl_add_u64 v[26:27], v[36:37], 0, v[0:1]
	v_lshl_add_u64 v[44:45], v[34:35], 0, v[0:1]
	v_mov_b64_e32 v[26:27], v[188:189]
	v_pk_mul_f32 v[48:49], v[28:29], v[26:27]
	v_mov_b64_e32 v[44:45], v[192:193]
	v_pk_mul_f32 v[46:47], v[28:29], v[44:45] op_sel:[1,0] op_sel_hi:[0,0]
	v_mov_b32_e32 v44, v27
	v_mul_f32_e32 v0, v39, v45
	v_pk_fma_f32 v[28:29], v[28:29], v[26:27], v[46:47] op_sel_hi:[1,0,1]
	v_pk_fma_f32 v[50:51], v[38:39], v[44:45], v[0:1] op_sel_hi:[1,1,0] neg_lo:[0,0,1] neg_hi:[0,0,1]
	v_mov_b32_e32 v26, v45
	v_mul_f32_e32 v0, v39, v27
	v_pk_fma_f32 v[26:27], v[38:39], v[26:27], v[0:1] op_sel_hi:[1,1,0]
	v_sub_f32_e32 v28, v48, v46
	v_mov_b32_e32 v38, v50
	v_mov_b32_e32 v39, v26

; template <int EPI>
; DI void gemm_epilogue(const Params& p, int layer, f32x4 (&acc)[2][2][4][2], int brow, int bcol, int pn, int wr, int wc,
;                       int fr, int fq, char* smem, int ksplit = -1) {
;     ...
;             for (int n = 0; n < 2; ++n) {
;               const int cih = (wc & 1) * 32 + fq * 8 + n * 4;
;               f32x4 v = acc[ai][bj][m][n];
;               if (normed) {
;                 f32x4 g = *(const f32x4*)(gq + cih);
;                 v = v * rs * g;
;                 if (latent) {
;                   const float2 cs = *(const float2*)(p.ropec + spos * 32 + (cih >> 1));
;                   const float2 sn = *(const float2*)(p.ropes + spos * 32 + (cih >> 1));
;                   f32x4 r;
;                   r[0] = v[0] * cs.x - v[1] * sn.x;
;                   r[1] = v[0] * sn.x + v[1] * cs.x;
;                   r[2] = v[2] * cs.y - v[3] * sn.y;
;                   r[3] = v[2] * sn.y + v[3] * cs.y;
;                   v = r;
;                 }
;                 if (pn == 9) v = v * 0.125f;
.LBB0_352:
	v_mov_b64_e32 v[30:31], v[168:169]
	v_mov_b64_e32 v[32:33], v[170:171]
	v_mov_b32_e32 v38, v28
	v_mov_b32_e32 v39, v28
	v_pk_mul_f32 v[24:25], v[24:25], v[38:39]
	v_pk_mul_f32 v[22:23], v[22:23], v[28:29]
	s_and_b64 vcc, exec, s[40:41]
	v_pk_mul_f32 v[24:25], v[24:25], v[32:33]
	v_pk_mul_f32 v[22:23], v[22:23], v[30:31]
	s_cbranch_vccnz .LBB0_354
	v_lshlrev_b32_e32 v0, 1, v140
	v_lshl_add_u64 v[30:31], v[36:37], 0, v[0:1]
	v_lshl_add_u64 v[32:33], v[34:35], 0, v[0:1]
	v_mov_b64_e32 v[30:31], v[186:187]
	v_pk_mul_f32 v[40:41], v[22:23], v[30:31]
	v_mov_b64_e32 v[32:33], v[190:191]
	v_pk_mul_f32 v[38:39], v[22:23], v[32:33] op_sel:[1,0] op_sel_hi:[0,0]
	v_mov_b32_e32 v32, v31
	v_mul_f32_e32 v0, v25, v33
	v_pk_fma_f32 v[22:23], v[22:23], v[30:31], v[38:39] op_sel_hi:[1,0,1]
	v_pk_fma_f32 v[42:43], v[24:25], v[32:33], v[0:1] op_sel_hi:[1,1,0] neg_lo:[0,0,1] neg_hi:[0,0,1]
	v_mov_b32_e32 v30, v33
	v_mul_f32_e32 v0, v25, v31
	v_pk_fma_f32 v[30:31], v[24:25], v[30:31], v[0:1] op_sel_hi:[1,1,0]
	v_sub_f32_e32 v22, v40, v38
	v_mov_b32_e32 v24, v42
	v_mov_b32_e32 v25, v30

; template <int EPI>
; DI void gemm_epilogue(const Params& p, int layer, f32x4 (&acc)[2][2][4][2], int brow, int bcol, int pn, int wr, int wc,
;                       int fr, int fq, char* smem, int ksplit = -1) {
;     ...
;             for (int n = 0; n < 2; ++n) {
;               const int cih = (wc & 1) * 32 + fq * 8 + n * 4;
;               f32x4 v = acc[ai][bj][m][n];
;               if (normed) {
;                 f32x4 g = *(const f32x4*)(gq + cih);
;                 v = v * rs * g;
;                 if (latent) {
;                   const float2 cs = *(const float2*)(p.ropec + spos * 32 + (cih >> 1));
;                   const float2 sn = *(const float2*)(p.ropes + spos * 32 + (cih >> 1));
;                   f32x4 r;
;                   r[0] = v[0] * cs.x - v[1] * sn.x;
;                   r[1] = v[0] * sn.x + v[1] * cs.x;
;                   r[2] = v[2] * cs.y - v[3] * sn.y;
;                   r[3] = v[2] * sn.y + v[3] * cs.y;
;                   v = r;
;                 }
;                 if (pn == 9) v = v * 0.125f;
.LBB0_355:
	v_mov_b64_e32 v[30:31], v[178:179]
	v_mov_b64_e32 v[32:33], v[180:181]
	v_mov_b32_e32 v38, v28
	v_mov_b32_e32 v39, v28
	v_pk_mul_f32 v[18:19], v[18:19], v[28:29]
	v_pk_mul_f32 v[20:21], v[20:21], v[38:39]
	s_and_b64 vcc, exec, s[40:41]
	v_pk_mul_f32 v[20:21], v[20:21], v[32:33]
	v_pk_mul_f32 v[18:19], v[18:19], v[30:31]
	s_cbranch_vccnz .LBB0_357
	v_lshlrev_b32_e32 v0, 1, v141
	v_lshl_add_u64 v[28:29], v[36:37], 0, v[0:1]
	v_lshl_add_u64 v[30:31], v[34:35], 0, v[0:1]
	v_mov_b64_e32 v[28:29], v[188:189]
	v_pk_mul_f32 v[34:35], v[18:19], v[28:29]
	v_mov_b64_e32 v[30:31], v[192:193]
	v_pk_mul_f32 v[32:33], v[18:19], v[30:31] op_sel:[1,0] op_sel_hi:[0,0]
	v_mov_b32_e32 v30, v29
	v_mul_f32_e32 v0, v21, v31
	v_pk_fma_f32 v[18:19], v[18:19], v[28:29], v[32:33] op_sel_hi:[1,0,1]
	v_pk_fma_f32 v[36:37], v[20:21], v[30:31], v[0:1] op_sel_hi:[1,1,0] neg_lo:[0,0,1] neg_hi:[0,0,1]
	v_mov_b32_e32 v28, v31
	v_mul_f32_e32 v0, v21, v29
	v_pk_fma_f32 v[28:29], v[20:21], v[28:29], v[0:1] op_sel_hi:[1,1,0]
	v_sub_f32_e32 v18, v34, v32
	v_mov_b32_e32 v20, v36
	v_mov_b32_e32 v21, v28

; template <int EPI>
; DI void gemm_epilogue(const Params& p, int layer, f32x4 (&acc)[2][2][4][2], int brow, int bcol, int pn, int wr, int wc,
;                       int fr, int fq, char* smem, int ksplit = -1) {
;     ...
;           const int rl = ai * 128 + wr * 64 + m * 16 + fr;
;           const int row = brow + rl;
;           const int spos = row & (SEQ - 1);
; #pragma unroll
;           for (int bj = 0; bj < 2; ++bj) {
;             const bool normed = (pn == 9) || (bj == 0);
;             float rs = 1.f;
;             if (normed) {
;               float tot = xch[rl * 8 + bj * 4 + wc] + xch[rl * 8 + bj * 4 + (wc ^ 1)];
;               rs = __builtin_amdgcn_rsqf(tot * (1.f / 64.f) + EPSN);
;             }
;             u32x4 o;
; #pragma unroll
;             for (int n = 0; n < 2; ++n) {
;               const int cih = (wc & 1) * 32 + fq * 8 + n * 4;
;               f32x4 v = acc[ai][bj][m][n];
;               if (normed) {
;                 f32x4 g = *(const f32x4*)(gq + cih);
;                 v = v * rs * g;
;                 if (latent) {
;                   const float2 cs = *(const float2*)(p.ropec + spos * 32 + (cih >> 1));
;                   const float2 sn = *(const float2*)(p.ropes + spos * 32 + (cih >> 1));
;                   f32x4 r;
;                   r[0] = v[0] * cs.x - v[1] * sn.x;
;                   r[1] = v[0] * sn.x + v[1] * cs.x;
;                   r[2] = v[2] * cs.y - v[3] * sn.y;
;                   r[3] = v[2] * sn.y + v[3] * cs.y;
;                   v = r;
;                 }
;                 if (pn == 9) v = v * 0.125f;
.LBB0_358:
	v_cvt_pk_bf16_f32 v22, v22, v23
	v_cvt_pk_bf16_f32 v23, v24, v25
	v_cvt_pk_bf16_f32 v24, v18, v19
	v_cvt_pk_bf16_f32 v25, v20, v21
	global_store_dwordx4 v[26:27], v[22:25], off offset:256
	v_mov_b64_e32 v[28:29], v[168:169]
	v_mov_b64_e32 v[30:31], v[170:171]
	v_add_u32_e32 v0, 0xb0, v154
	v_lshlrev_b32_e32 v18, 3, v0
	v_or_b32_e32 v25, s13, v18
	v_bitop3_b32 v18, v18, 1, s13 bitop3:0x36
	v_lshl_add_u32 v24, v25, 2, s24
	v_lshl_add_u32 v18, v18, 2, s24
	ds_read_b32 v19, v24
	ds_read_b32 v18, v18
	v_add_u32_e32 v26, s22, v0
	v_lshlrev_b32_e32 v0, 7, v26
	v_readlane_b32 s60, v254, 45
	v_and_b32_e32 v0, 0x3ff80, v0
	s_waitcnt lgkmcnt(0)
	v_add_f32_e32 v18, v19, v18
	v_fmamk_f32 v18, v18, 0x3c800000, v236
	v_rsq_f32_e32 v22, v18
	v_readlane_b32 s66, v254, 51
	v_readlane_b32 s67, v254, 52
	v_readlane_b32 s68, v254, 53
	v_readlane_b32 s69, v254, 54
	v_pk_mul_f32 v[14:15], v[14:15], v[22:23] op_sel_hi:[1,0]
	v_pk_mul_f32 v[16:17], v[16:17], v[22:23] op_sel_hi:[1,0]
	s_and_b64 vcc, exec, s[40:41]
	v_lshl_add_u64 v[20:21], s[66:67], 0, v[0:1]
	v_lshl_add_u64 v[18:19], s[68:69], 0, v[0:1]
	v_lshl_add_u64 v[184:185], v[20:21], 0, v[182:183]
	global_load_dwordx4 v[186:189], v[184:185], off
	v_lshl_add_u64 v[184:185], v[18:19], 0, v[182:183]
	global_load_dwordx4 v[190:193], v[184:185], off
	v_readlane_b32 s61, v254, 46
	v_readlane_b32 s62, v254, 47
	v_readlane_b32 s63, v254, 48
	v_readlane_b32 s64, v254, 49
	v_readlane_b32 s65, v254, 50
	v_readlane_b32 s70, v254, 55
	v_readlane_b32 s71, v254, 56
	v_readlane_b32 s72, v254, 57
	v_readlane_b32 s73, v254, 58
	v_readlane_b32 s74, v254, 59
	v_readlane_b32 s75, v254, 60
	v_pk_mul_f32 v[16:17], v[30:31], v[16:17]
	v_pk_mul_f32 v[14:15], v[28:29], v[14:15]
	s_cbranch_vccnz .LBB0_360
	v_lshlrev_b32_e32 v0, 1, v140
	v_lshl_add_u64 v[28:29], v[20:21], 0, v[0:1]
	v_lshl_add_u64 v[30:31], v[18:19], 0, v[0:1]
	s_waitcnt vmcnt(0)
	v_mov_b64_e32 v[28:29], v[186:187]
	v_pk_mul_f32 v[34:35], v[14:15], v[28:29]
	v_mov_b64_e32 v[30:31], v[190:191]
	v_pk_mul_f32 v[32:33], v[14:15], v[30:31] op_sel:[1,0] op_sel_hi:[0,0]
	v_mov_b32_e32 v30, v29
	v_mul_f32_e32 v0, v17, v31
	v_pk_fma_f32 v[14:15], v[14:15], v[28:29], v[32:33] op_sel_hi:[1,0,1]
	v_pk_fma_f32 v[36:37], v[16:17], v[30:31], v[0:1] op_sel_hi:[1,1,0] neg_lo:[0,0,1] neg_hi:[0,0,1]
	v_mov_b32_e32 v28, v31
	v_mul_f32_e32 v0, v17, v29
	v_pk_fma_f32 v[28:29], v[16:17], v[28:29], v[0:1] op_sel_hi:[1,1,0]
	v_sub_f32_e32 v14, v34, v32
	v_mov_b32_e32 v16, v36
	v_mov_b32_e32 v17, v28
.LBB0_360:
	v_mov_b64_e32 v[28:29], v[178:179]
	v_mov_b64_e32 v[30:31], v[180:181]
	v_mov_b32_e32 v23, v22
	v_mov_b32_e32 v32, v22
	v_mov_b32_e32 v33, v22
	v_pk_mul_f32 v[12:13], v[12:13], v[32:33]
	v_pk_mul_f32 v[10:11], v[10:11], v[22:23]
	s_and_b64 vcc, exec, s[40:41]
	v_pk_mul_f32 v[12:13], v[12:13], v[30:31]
	v_pk_mul_f32 v[10:11], v[10:11], v[28:29]
	s_cbranch_vccnz .LBB0_362
	v_lshlrev_b32_e32 v0, 1, v141
	v_lshl_add_u64 v[22:23], v[20:21], 0, v[0:1]
	v_lshl_add_u64 v[28:29], v[18:19], 0, v[0:1]
	v_mov_b64_e32 v[22:23], v[188:189]
	v_pk_mul_f32 v[32:33], v[10:11], v[22:23]
	v_mov_b64_e32 v[28:29], v[192:193]
	v_pk_mul_f32 v[30:31], v[10:11], v[28:29] op_sel:[1,0] op_sel_hi:[0,0]
	v_mov_b32_e32 v28, v23
	v_mul_f32_e32 v0, v13, v29
	v_pk_fma_f32 v[10:11], v[10:11], v[22:23], v[30:31] op_sel_hi:[1,0,1]
	v_pk_fma_f32 v[34:35], v[12:13], v[28:29], v[0:1] op_sel_hi:[1,1,0] neg_lo:[0,0,1] neg_hi:[0,0,1]
	v_mov_b32_e32 v22, v29
	v_mul_f32_e32 v0, v13, v23
	v_pk_fma_f32 v[22:23], v[12:13], v[22:23], v[0:1] op_sel_hi:[1,1,0]
	v_sub_f32_e32 v10, v32, v30
	v_mov_b32_e32 v12, v34
	v_mov_b32_e32 v13, v22

; template <int EPI>
; DI void gemm_epilogue(const Params& p, int layer, f32x4 (&acc)[2][2][4][2], int brow, int bcol, int pn, int wr, int wc,
;                       int fr, int fq, char* smem, int ksplit = -1) {
;     ...
;             for (int n = 0; n < 2; ++n) {
;               const int cih = (wc & 1) * 32 + fq * 8 + n * 4;
;               f32x4 v = acc[ai][bj][m][n];
;               if (normed) {
;                 f32x4 g = *(const f32x4*)(gq + cih);
;                 v = v * rs * g;
;                 if (latent) {
;                   const float2 cs = *(const float2*)(p.ropec + spos * 32 + (cih >> 1));
;                   const float2 sn = *(const float2*)(p.ropes + spos * 32 + (cih >> 1));
;                   f32x4 r;
;                   r[0] = v[0] * cs.x - v[1] * sn.x;
;                   r[1] = v[0] * sn.x + v[1] * cs.x;
;                   r[2] = v[2] * cs.y - v[3] * sn.y;
;                   r[3] = v[2] * sn.y + v[3] * cs.y;
;                   v = r;
;                 }
;                 if (pn == 9) v = v * 0.125f;
.LBB0_366:
	v_mov_b64_e32 v[12:13], v[168:169]
	v_mov_b64_e32 v[14:15], v[170:171]
	v_mov_b32_e32 v16, v10
	v_mov_b32_e32 v17, v10
	v_pk_mul_f32 v[8:9], v[8:9], v[16:17]
	v_pk_mul_f32 v[6:7], v[6:7], v[10:11]
	s_and_b64 vcc, exec, s[40:41]
	v_pk_mul_f32 v[8:9], v[8:9], v[14:15]
	v_pk_mul_f32 v[6:7], v[6:7], v[12:13]
	s_cbranch_vccnz .LBB0_368
	v_lshlrev_b32_e32 v0, 1, v140
	v_lshl_add_u64 v[12:13], v[20:21], 0, v[0:1]
	v_lshl_add_u64 v[14:15], v[18:19], 0, v[0:1]
	v_mov_b64_e32 v[12:13], v[186:187]
	v_pk_mul_f32 v[22:23], v[6:7], v[12:13]
	v_mov_b64_e32 v[14:15], v[190:191]
	v_pk_mul_f32 v[16:17], v[6:7], v[14:15] op_sel:[1,0] op_sel_hi:[0,0]
	v_mov_b32_e32 v14, v13
	v_mul_f32_e32 v0, v9, v15
	v_pk_fma_f32 v[6:7], v[6:7], v[12:13], v[16:17] op_sel_hi:[1,0,1]
	v_pk_fma_f32 v[24:25], v[8:9], v[14:15], v[0:1] op_sel_hi:[1,1,0] neg_lo:[0,0,1] neg_hi:[0,0,1]
	v_mov_b32_e32 v12, v15
	v_mul_f32_e32 v0, v9, v13
	v_pk_fma_f32 v[12:13], v[8:9], v[12:13], v[0:1] op_sel_hi:[1,1,0]
	v_sub_f32_e32 v6, v22, v16
	v_mov_b32_e32 v8, v24
	v_mov_b32_e32 v9, v12

; template <int EPI>
; DI void gemm_epilogue(const Params& p, int layer, f32x4 (&acc)[2][2][4][2], int brow, int bcol, int pn, int wr, int wc,
;                       int fr, int fq, char* smem, int ksplit = -1) {
;     ...
;             for (int n = 0; n < 2; ++n) {
;               const int cih = (wc & 1) * 32 + fq * 8 + n * 4;
;               f32x4 v = acc[ai][bj][m][n];
;               if (normed) {
;                 f32x4 g = *(const f32x4*)(gq + cih);
;                 v = v * rs * g;
;                 if (latent) {
;                   const float2 cs = *(const float2*)(p.ropec + spos * 32 + (cih >> 1));
;                   const float2 sn = *(const float2*)(p.ropes + spos * 32 + (cih >> 1));
;                   f32x4 r;
;                   r[0] = v[0] * cs.x - v[1] * sn.x;
;                   r[1] = v[0] * sn.x + v[1] * cs.x;
;                   r[2] = v[2] * cs.y - v[3] * sn.y;
;                   r[3] = v[2] * sn.y + v[3] * cs.y;
;                   v = r;
;                 }
;                 if (pn == 9) v = v * 0.125f;
.LBB0_369:
	v_mov_b64_e32 v[12:13], v[178:179]
	v_mov_b64_e32 v[14:15], v[180:181]
	v_mov_b32_e32 v16, v10
	v_mov_b32_e32 v17, v10
	v_pk_mul_f32 v[2:3], v[2:3], v[10:11]
	v_pk_mul_f32 v[4:5], v[4:5], v[16:17]
	s_and_b64 vcc, exec, s[40:41]
	v_pk_mul_f32 v[4:5], v[4:5], v[14:15]
	v_pk_mul_f32 v[2:3], v[2:3], v[12:13]
	s_cbranch_vccnz .LBB0_371
	v_lshlrev_b32_e32 v0, 1, v141
	v_lshl_add_u64 v[10:11], v[20:21], 0, v[0:1]
	v_lshl_add_u64 v[12:13], v[18:19], 0, v[0:1]
	v_mov_b64_e32 v[10:11], v[188:189]
	v_pk_mul_f32 v[16:17], v[2:3], v[10:11]
	v_mov_b64_e32 v[12:13], v[192:193]
	v_pk_mul_f32 v[14:15], v[2:3], v[12:13] op_sel:[1,0] op_sel_hi:[0,0]
	v_mov_b32_e32 v12, v11
	v_mul_f32_e32 v0, v5, v13
	v_pk_fma_f32 v[2:3], v[2:3], v[10:11], v[14:15] op_sel_hi:[1,0,1]
	v_pk_fma_f32 v[18:19], v[4:5], v[12:13], v[0:1] op_sel_hi:[1,1,0] neg_lo:[0,0,1] neg_hi:[0,0,1]
	v_mov_b32_e32 v10, v13
	v_mul_f32_e32 v0, v5, v11
	v_pk_fma_f32 v[10:11], v[4:5], v[10:11], v[0:1] op_sel_hi:[1,1,0]
	v_sub_f32_e32 v2, v16, v14
	v_mov_b32_e32 v4, v18
	v_mov_b32_e32 v5, v10
